# attention: two query blocks (units i, i+1) per wave share each K/V fragment set; unit epilogue run twice
# speedup vs baseline: 1.0149x; 1.0149x over previous
; template <int VAR>
; __device__ __forceinline__ void attn_unit(const Args& a, int l, int b, int h, int qrow0  , bool ctxu, const bf16* Z, bf16* Y, LAS unsigned char* lds) {
;     ...
;     float lam, omli;
;     { float s1 = 0.f, s2 = 0.f;
;       for (int i = 0; i < 32; ++i) { s1 += a.lam_q1[l * 32 + i] * a.lam_k1[l * 32 + i]; s2 += a.lam_q2[l * 32 + i] * a.lam_k2[l * 32 + i]; }
;       const float li = 0.8f - 0.6f * expf(-0.3f * (float)l); lam = expf(s1) - expf(s2) + li; omli = 1.f - li; }
.LBB0_426:
	v_readlane_b32 s8, v254, 46
	v_readlane_b32 s9, v254, 47
	s_andn2_b64 vcc, exec, s[8:9]
	s_cbranch_vccnz .LBB0_464
	v_cvt_f32_u32_e32 v0, s68
	s_mov_b32 s8, 0x3fb8aa3b
	s_lshl_b32 s72, s68, 5
	v_readlane_b32 s36, v252, 27
	v_mul_f32_e32 v0, 0xbe99999a, v0
	v_mul_f32_e32 v1, 0x3fb8aa3b, v0
	v_fma_f32 v2, v0, s8, -v1
	v_rndne_f32_e32 v3, v1
	v_fmac_f32_e32 v2, 0x32a5705f, v0
	v_sub_f32_e32 v1, v1, v3
	v_add_f32_e32 v1, v1, v2
	v_cvt_i32_f32_e32 v3, v3
	v_exp_f32_e32 v1, v1
	s_mov_b32 s8, 0xc2ce8ed0
	v_cmp_ngt_f32_e32 vcc, s8, v0
	s_mov_b32 s8, 0x42b17218
	v_ldexp_f32 v1, v1, v3
	v_cndmask_b32_e32 v1, 0, v1, vcc
	v_cmp_nlt_f32_e32 vcc, s8, v0
	s_lshl_b64 s[8:9], s[72:73], 2
	v_readlane_b32 s40, v252, 31
	v_readlane_b32 s46, v252, 37
	v_readlane_b32 s41, v252, 32
	v_readlane_b32 s47, v252, 38
	s_add_u32 s40, s46, s8
	v_readlane_b32 s42, v252, 33
	v_readlane_b32 s48, v252, 39
	s_addc_u32 s41, s47, s9
	v_readlane_b32 s43, v252, 34
	v_readlane_b32 s49, v252, 40
	s_add_u32 s42, s48, s8
	v_readlane_b32 s44, v252, 35
	v_readlane_b32 s50, v252, 41
	s_addc_u32 s43, s49, s9
	v_readlane_b32 s45, v252, 36
	v_readlane_b32 s51, v252, 42
	s_add_u32 s44, s50, s8
	v_cndmask_b32_e32 v0, v245, v1, vcc
	s_addc_u32 s45, s51, s9
	v_readlane_b32 s76, v252, 43
	v_fmamk_f32 v221, v0, 0xbf19999a, v220
	v_readlane_b32 s77, v252, 44
	s_add_u32 s46, s76, s8
	v_sub_f32_e32 v226, 1.0, v221
	s_addc_u32 s47, s77, s9
	s_lshl_b32 s58, s68, 6
	s_mov_b32 s59, 0
	global_load_dwordx4 v[0:3], v217, s[40:41]
	global_load_dwordx4 v[4:7], v217, s[40:41] offset:16
	global_load_dwordx4 v[8:11], v217, s[40:41] offset:32
	global_load_dwordx4 v[12:15], v217, s[40:41] offset:48
	global_load_dwordx4 v[16:19], v217, s[40:41] offset:64
	global_load_dwordx4 v[20:23], v217, s[40:41] offset:80
	global_load_dwordx4 v[24:27], v217, s[40:41] offset:96
	global_load_dwordx4 v[28:31], v217, s[40:41] offset:112
	global_load_dwordx4 v[32:35], v217, s[42:43]
	global_load_dwordx4 v[36:39], v217, s[42:43] offset:16
	global_load_dwordx4 v[40:43], v217, s[42:43] offset:32
	global_load_dwordx4 v[44:47], v217, s[42:43] offset:48
	global_load_dwordx4 v[48:51], v217, s[42:43] offset:64
	global_load_dwordx4 v[52:55], v217, s[42:43] offset:80
	global_load_dwordx4 v[56:59], v217, s[42:43] offset:96
	global_load_dwordx4 v[60:63], v217, s[42:43] offset:112
	global_load_dwordx4 v[64:67], v217, s[44:45]
	global_load_dwordx4 v[68:71], v217, s[44:45] offset:16
	global_load_dwordx4 v[72:75], v217, s[44:45] offset:32
	global_load_dwordx4 v[76:79], v217, s[44:45] offset:48
	global_load_dwordx4 v[80:83], v217, s[44:45] offset:64
	global_load_dwordx4 v[84:87], v217, s[44:45] offset:80
	global_load_dwordx4 v[88:91], v217, s[44:45] offset:96
	global_load_dwordx4 v[92:95], v217, s[44:45] offset:112
	global_load_dwordx4 v[96:99], v217, s[46:47]
	global_load_dwordx4 v[100:103], v217, s[46:47] offset:16
	global_load_dwordx4 v[104:107], v217, s[46:47] offset:32
	global_load_dwordx4 v[108:111], v217, s[46:47] offset:48
	global_load_dwordx4 v[112:115], v217, s[46:47] offset:64
	global_load_dwordx4 v[116:119], v217, s[46:47] offset:80
	global_load_dwordx4 v[120:123], v217, s[46:47] offset:96
	global_load_dwordx4 v[124:127], v217, s[46:47] offset:112
	s_mov_b32 s50, 0x3fb8aa3b
	s_mov_b32 s51, 0xc2ce8ed0
	s_mov_b32 s93, 0x42b17218
	s_waitcnt vmcnt(0)
	v_fma_f32 v128, v0, v32, 0
	v_fmac_f32_e32 v128, v1, v33
	v_fmac_f32_e32 v128, v2, v34
	v_fmac_f32_e32 v128, v3, v35
	v_fmac_f32_e32 v128, v4, v36
	v_fmac_f32_e32 v128, v5, v37
	v_fmac_f32_e32 v128, v6, v38
	v_fmac_f32_e32 v128, v7, v39
	v_fmac_f32_e32 v128, v8, v40
	v_fmac_f32_e32 v128, v9, v41
	v_fmac_f32_e32 v128, v10, v42
	v_fmac_f32_e32 v128, v11, v43
	v_fmac_f32_e32 v128, v12, v44
	v_fmac_f32_e32 v128, v13, v45
	v_fmac_f32_e32 v128, v14, v46
	v_fmac_f32_e32 v128, v15, v47
	v_fmac_f32_e32 v128, v16, v48
	v_fmac_f32_e32 v128, v17, v49
	v_fmac_f32_e32 v128, v18, v50
	v_fmac_f32_e32 v128, v19, v51
	v_fmac_f32_e32 v128, v20, v52
	v_fmac_f32_e32 v128, v21, v53
	v_fmac_f32_e32 v128, v22, v54
	v_fmac_f32_e32 v128, v23, v55
	v_fmac_f32_e32 v128, v24, v56
	v_fmac_f32_e32 v128, v25, v57
	v_fmac_f32_e32 v128, v26, v58
	v_fmac_f32_e32 v128, v27, v59
	v_fmac_f32_e32 v128, v28, v60
	v_fmac_f32_e32 v128, v29, v61
	v_fmac_f32_e32 v128, v30, v62
	v_fmac_f32_e32 v128, v31, v63
	v_fma_f32 v129, v64, v96, 0
	v_fmac_f32_e32 v129, v65, v97
	v_fmac_f32_e32 v129, v66, v98
	v_fmac_f32_e32 v129, v67, v99
	v_fmac_f32_e32 v129, v68, v100
	v_fmac_f32_e32 v129, v69, v101
	v_fmac_f32_e32 v129, v70, v102
	v_fmac_f32_e32 v129, v71, v103
	v_fmac_f32_e32 v129, v72, v104
	v_fmac_f32_e32 v129, v73, v105
	v_fmac_f32_e32 v129, v74, v106
	v_fmac_f32_e32 v129, v75, v107
	v_fmac_f32_e32 v129, v76, v108
	v_fmac_f32_e32 v129, v77, v109
	v_fmac_f32_e32 v129, v78, v110
	v_fmac_f32_e32 v129, v79, v111
	v_fmac_f32_e32 v129, v80, v112
	v_fmac_f32_e32 v129, v81, v113
	v_fmac_f32_e32 v129, v82, v114
	v_fmac_f32_e32 v129, v83, v115
	v_fmac_f32_e32 v129, v84, v116
	v_fmac_f32_e32 v129, v85, v117
	v_fmac_f32_e32 v129, v86, v118
	v_fmac_f32_e32 v129, v87, v119
	v_fmac_f32_e32 v129, v88, v120
	v_fmac_f32_e32 v129, v89, v121
	v_fmac_f32_e32 v129, v90, v122
	v_fmac_f32_e32 v129, v91, v123
	v_fmac_f32_e32 v129, v92, v124
	v_fmac_f32_e32 v129, v93, v125
	v_fmac_f32_e32 v129, v94, v126
	v_fmac_f32_e32 v129, v95, v127
	v_mul_f32_e32 v132, 0x3fb8aa3b, v128
	v_fma_f32 v133, v128, s50, -v132
	v_rndne_f32_e32 v134, v132
	v_fmac_f32_e32 v133, 0x32a5705f, v128
	v_sub_f32_e32 v132, v132, v134
	v_add_f32_e32 v132, v132, v133
	v_exp_f32_e32 v132, v132
	v_cvt_i32_f32_e32 v133, v134
	v_cmp_ngt_f32_e32 vcc, s51, v128
	v_ldexp_f32 v132, v132, v133
	s_nop 1
	v_cndmask_b32_e32 v132, 0, v132, vcc
	v_cmp_nlt_f32_e32 vcc, s93, v128
	s_nop 1
	v_cndmask_b32_e32 v130, v245, v132, vcc
	v_mul_f32_e32 v132, 0x3fb8aa3b, v129
	v_fma_f32 v133, v129, s50, -v132
	v_rndne_f32_e32 v134, v132
	v_fmac_f32_e32 v133, 0x32a5705f, v129
	v_sub_f32_e32 v132, v132, v134
	v_add_f32_e32 v132, v132, v133
	v_exp_f32_e32 v132, v132
	v_cvt_i32_f32_e32 v133, v134
	v_cmp_ngt_f32_e32 vcc, s51, v129
	v_ldexp_f32 v132, v132, v133
	s_nop 1
	v_cndmask_b32_e32 v132, 0, v132, vcc
	v_cmp_nlt_f32_e32 vcc, s93, v129
	s_nop 1
	v_cndmask_b32_e32 v131, v245, v132, vcc
	v_sub_f32_e32 v130, v130, v131
	v_add_f32_e32 v167, v221, v130
	v_readlane_b32 s8, v254, 44
	v_readlane_b32 s37, v252, 28
	v_readlane_b32 s38, v252, 29
	v_readlane_b32 s39, v252, 30
	v_readlane_b32 s78, v252, 45
	v_readlane_b32 s79, v252, 46
	v_readlane_b32 s80, v252, 47
	v_readlane_b32 s81, v252, 48
	v_readlane_b32 s82, v252, 49
	v_readlane_b32 s83, v252, 50
	v_readlane_b32 s84, v252, 51
	v_readlane_b32 s85, v252, 52
	v_readlane_b32 s86, v252, 53
	v_readlane_b32 s87, v252, 54
	v_readlane_b32 s88, v252, 55
	v_readlane_b32 s89, v252, 56
	v_readlane_b32 s90, v252, 57
	v_readlane_b32 s91, v252, 58
	s_branch .LBB0_429

; #define LAS __attribute__((address_space(3)))
; __device__ __forceinline__ int opaque_tid() { int t = threadIdx.x; asm volatile("" : "+v"(t)); return t; }
; __device__ __forceinline__ int v_st_nat(int k, int c) { return ((k >> 3) * 2 + (c >> 5)) * 512 + ((k & 7) * 32 + (c & 31)) * 2; }
; __device__ __forceinline__ int v_rd_base(int lane) { return ((lane & 3) << 3) | (((lane >> 2) & 3) << 6) | (((lane >> 4) & 1) << 5) | (((lane >> 5) & 1) << 8); }
; #define AT_LOAD(K0, K1, V0, V1, T) do { const size_t e_ = (size_t)(128 * (T) + sr) * 64 + sc; \
;         K0 = *(const bf16x8*)(kcp + e_); V0 = *(const bf16x8*)(vcp + e_); K1 = *(const bf16x8*)(kcp + e_ + 64 * 64); V1 = *(const bf16x8*)(vcp + e_ + 64 * 64); } while (0)
; #define AT_STORE(K0, K1, V0, V1, BUF) do { *(LAS bf16x8*)(lds + AT_K + (BUF) * AT_KB + kst0) = K0; *(LAS bf16x8*)(lds + AT_K + (BUF) * AT_KB + kst1) = K1; \
;         *(LAS bf16x8*)(lds + AT_V + (BUF) * AT_VB + vst0) = V0; *(LAS bf16x8*)(lds + AT_V + (BUF) * AT_VB + vst1) = V1; } while (0)
; template <int VAR>
; __device__ __forceinline__ void attn_unit(const Args& a, int l, int b, int h, int qrow0  , bool ctxu, const bf16* Z, bf16* Y, LAS unsigned char* lds) {
;     const int tid = opaque_tid(), lane = tid & 63, wave = __builtin_amdgcn_readfirstlane(tid >> 6), r32 = lane & 31, hi = lane >> 5;
;     const int comp = wave >> 2, wq = wave & 3;
;     const int NT = ctxu ? 2 : 66;
;     const bf16* kcp = (const bf16*)(a.ws + WS_KC) + (size_t)(b * 4 + h) * 8448 * 64; const bf16* vcp = (const bf16*)(a.ws + WS_VC) + (size_t)(b * 4 + h) * 8448 * 64;
;     bf16x8 q0, q1;
;     { const bf16* qp = Z + (size_t)(qrow0 + wq * 32 + r32) * DIN + 512 + h * 64 + comp * 32 + hi * 8; q0 = *(const bf16x8*)(qp); q1 = *(const bf16x8*)(qp + 16); }
;     const int sr = tid >> 3, sc = (tid & 7) * 8;
;     const int kst0 = sr * 144 + sc * 2, kst1 = kst0 + 64 * 144, vst0 = v_st_nat(sr, sc), vst1 = v_st_nat(sr + 64, sc);
;     const int vb0 = (int)(unsigned)(uintptr_t)(lds + AT_V) + v_rd_base(lane);
;     LAS float* wsf = (LAS float*)(lds + AT_WS) + wave * 64;
;     f32x16 negm = f32x16{}, o0 = f32x16{}, o1 = f32x16{}, lacc = f32x16{};
;     float m = 0.f;
;     bf16x8 ka0, ka1, va0, va1, kb0, kb1, vb0_, vb1_;
;     ...
;     AT_LOAD(ka0, ka1, va0, va1, 0); AT_LOAD(kb0, kb1, vb0_, vb1_, 1); AT_STORE(ka0, ka1, va0, va1, 0);
.LBB0_429:
	s_ashr_i32 s9, s8, 6
	s_add_i32 s14, s9, s17
	s_lshl_b32 s9, s14, 11
	s_lshl_b32 s8, s8, 7
	v_mov_b32_e32 v12, v219
	s_and_b32 s9, s9, 0xffffe000
	s_and_b32 s8, s8, 0x1f80
	s_or_b32 s12, s8, s9
	v_readfirstlane_b32 s29, v12
	s_ashr_i32 s8, s29, 8
	s_bfe_u32 s9, s29, 0x20006
	s_mul_i32 s15, s14, 0x108000
	v_readlane_b32 s16, v254, 11
	v_ashrrev_i32_e32 v0, 3, v12
	v_lshlrev_b32_e32 v13, 3, v12
	s_mul_hi_i32 s13, s14, 0x108000
	s_add_u32 s36, s16, s15
	v_readlane_b32 s16, v254, 12
	v_and_b32_e32 v228, 56, v13
	v_ashrrev_i32_e32 v1, 31, v0
	s_addc_u32 s37, s16, s13
	v_readlane_b32 s16, v254, 13
	v_lshlrev_b32_e32 v2, 1, v228
	v_lshlrev_b64 v[4:5], 7, v[0:1]
	s_add_u32 s38, s16, s15
	v_readlane_b32 s15, v254, 14
	v_or_b32_e32 v6, v4, v2
	v_mov_b32_e32 v7, v5
	s_addc_u32 s39, s15, s13
	v_lshl_add_u64 v[8:9], s[36:37], 0, v[6:7]
	v_lshl_add_u64 v[10:11], s[38:39], 0, v[6:7]
	v_add_co_u32_e32 v8, vcc, s62, v8
	s_lshl_b32 s13, s9, 5
	s_nop 0
	v_addc_co_u32_e32 v9, vcc, 0, v9, vcc
	v_add_co_u32_e32 v8, vcc, s62, v10
	v_and_b32_e32 v247, 31, v12
	s_nop 0
	v_addc_co_u32_e32 v9, vcc, 0, v11, vcc
	s_or_b32 s60, s13, s12
	v_or_b32_e32 v1, s60, v247
	v_mov_b64_e32 v[8:9], s[0:1]
	v_mad_i64_i32 v[8:9], s[12:13], v1, s30, v[8:9]
	s_lshl_b32 s12, s14, 6
	s_and_b32 s28, s12, 0xc0
	s_lshl_b32 s72, s28, 1
	s_lshl_b32 s12, s8, 5
	v_bfe_u32 v248, v12, 5, 1
	v_lshl_add_u64 v[8:9], v[8:9], 0, s[72:73]
	s_ashr_i32 s13, s12, 31
	v_lshl_add_u64 v[8:9], s[12:13], 1, v[8:9]
	v_lshlrev_b32_e32 v216, 4, v248
	s_mov_b64 s[48:49], 0x4000
	v_lshl_add_u64 v[8:9], v[8:9], 0, v[216:217]
	v_lshl_add_u64 v[6:7], v[6:7], 0, s[48:49]
	global_load_dwordx4 v[136:139], v[8:9], off offset:1024
	global_load_dwordx4 v[140:143], v[8:9], off offset:1056
	s_mov_b32 s50, 0x1400000
	v_add_co_u32_e32 v8, vcc, s50, v8
	s_nop 1
	v_addc_co_u32_e32 v9, vcc, 0, v9, vcc
	global_load_dwordx4 v[150:153], v[8:9], off offset:1024
	global_load_dwordx4 v[154:157], v[8:9], off offset:1056
	v_lshl_add_u64 v[8:9], s[36:37], 0, v[6:7]
	v_lshl_add_u64 v[6:7], s[38:39], 0, v[6:7]
	v_add_co_u32_e32 v8, vcc, s62, v8
	s_movk_i32 s15, 0x90
	s_nop 0
	v_addc_co_u32_e32 v9, vcc, 0, v9, vcc
	v_add_co_u32_e32 v6, vcc, s62, v6
	v_mad_u64_u32 v[2:3], s[12:13], v0, s15, v[2:3]
	s_nop 0
	v_addc_co_u32_e32 v7, vcc, 0, v7, vcc
	v_lshlrev_b32_e32 v10, 5, v0
	v_and_b32_e32 v11, 24, v13
	s_movk_i32 s13, 0xe0
	v_add_u32_e32 v0, 64, v0
	v_lshrrev_b32_e32 v1, 5, v12
	v_bfe_u32 v3, v13, 5, 1
	s_mov_b32 s12, 0x7ffffe
	v_and_or_b32 v6, v10, s13, v11
	v_lshrrev_b32_e32 v0, 2, v0
	v_and_or_b32 v1, v1, s12, v3
	v_lshlrev_b32_e32 v6, 1, v6
	v_and_or_b32 v0, v0, s12, v3
	v_and_b32_e32 v227, 63, v12
	v_lshl_or_b32 v1, v1, 9, v6
	v_lshl_or_b32 v0, v0, 9, v6
	v_lshlrev_b32_e32 v6, 4, v12
	v_lshlrev_b32_e32 v3, 3, v227
	v_and_b32_e32 v6, 0xc0, v6
	v_lshlrev_b32_e32 v7, 1, v12
	v_and_or_b32 v6, v3, 24, v6
	v_and_b32_e32 v7, 32, v7
	v_and_b32_e32 v3, 0x100, v3
	v_or3_b32 v3, v6, v7, v3
	s_add_i32 s12, 0, 0x9000
	v_add_u32_e32 v249, s12, v3
	s_and_b32 s12, s29, 0x3fffffc0
	s_lshl_b32 s12, s12, 2
	s_add_i32 s31, s12, 0
	s_lshl_b32 s12, s8, 6
	s_add_i32 s12, s12, 0
	v_add_u32_e32 v229, 0, v0
	v_mov_b32_e32 v0, s12
	s_add_i32 s12, 0, 0xd000
	v_add_u32_e32 v251, 0, v1
	v_mad_u32_u24 v16, v247, s15, v0
	v_add_u32_e32 v233, s12, v3
	v_mad_i64_i32 v[0:1], s[12:13], s14, v246, v[4:5]
	v_add_u32_e32 v250, 0, v2
	v_and_b32_e32 v2, 7, v12
	v_readlane_b32 s12, v255, 17
	v_lshl_or_b32 v0, v2, 4, v0
	v_readlane_b32 s13, v255, 18
	v_mov_b32_e32 v14, v217
	v_mov_b32_e32 v15, v217
	s_add_i32 s31, s31, 0x11000
	v_lshl_add_u64 v[230:231], s[12:13], 0, v[0:1]
	v_mov_b32_e32 v0, v217
	v_mov_b32_e32 v1, v217
	v_mov_b32_e32 v2, v217
	v_mov_b32_e32 v3, v217
	v_mov_b32_e32 v4, v217
	v_mov_b32_e32 v5, v217
	v_mov_b32_e32 v6, v217
	v_mov_b32_e32 v7, v217
	v_mov_b32_e32 v8, v217
	v_mov_b32_e32 v9, v217
	v_mov_b32_e32 v10, v217
	v_mov_b32_e32 v11, v217
	v_mov_b32_e32 v12, v217
	v_mov_b32_e32 v13, v217
	v_mov_b32_e32 v234, 0
	v_add_u32_e32 v235, v16, v216
	v_mov_b64_e32 v[30:31], v[14:15]
	s_waitcnt vmcnt(0)
	v_mov_b64_e32 v[46:47], v[14:15]
	v_cmp_gt_u32_e64 s[38:39], 32, v227
	v_lshl_add_u32 v232, v247, 2, s31
	s_mov_b64 s[36:37], 0
	s_mov_b32 s33, 0
	v_mov_b64_e32 v[28:29], v[12:13]
	v_mov_b64_e32 v[26:27], v[10:11]
	v_mov_b64_e32 v[24:25], v[8:9]
	v_mov_b64_e32 v[22:23], v[6:7]
	v_mov_b64_e32 v[20:21], v[4:5]
	v_mov_b64_e32 v[18:19], v[2:3]
	v_mov_b64_e32 v[16:17], v[0:1]
	v_mov_b64_e32 v[44:45], v[12:13]
	v_mov_b64_e32 v[42:43], v[10:11]
	v_mov_b64_e32 v[40:41], v[8:9]
	v_mov_b64_e32 v[38:39], v[6:7]
	v_mov_b64_e32 v[36:37], v[4:5]
	v_mov_b64_e32 v[34:35], v[2:3]
	v_mov_b64_e32 v[32:33], v[0:1]
	s_waitcnt vmcnt(0)
	v_mov_b32_e32 v64, 0
	v_mov_b32_e32 v65, v234
	v_mov_b32_e32 v66, v234
	v_mov_b32_e32 v67, v234
	v_mov_b32_e32 v68, v234
	v_mov_b32_e32 v69, v234
	v_mov_b32_e32 v70, v234
	v_mov_b32_e32 v71, v234
	v_mov_b32_e32 v72, v234
	v_mov_b32_e32 v73, v234
	v_mov_b32_e32 v74, v234
	v_mov_b32_e32 v75, v234
	v_mov_b32_e32 v76, v234
	v_mov_b32_e32 v77, v234
	v_mov_b32_e32 v78, v234
	v_mov_b32_e32 v48, 0
	v_readlane_b32 s14, v255, 19
	v_readlane_b32 s15, v255, 20
	s_branch .LBB0_431
; #define LAS __attribute__((address_space(3)))
; #define AT_LOAD(K0, K1, V0, V1, T) do { const size_t e_ = (size_t)(128 * (T) + sr) * 64 + sc; \
;         K0 = *(const bf16x8*)(kcp + e_); V0 = *(const bf16x8*)(vcp + e_); K1 = *(const bf16x8*)(kcp + e_ + 64 * 64); V1 = *(const bf16x8*)(vcp + e_ + 64 * 64); } while (0)
; #define AT_STORE(K0, K1, V0, V1, BUF) do { *(LAS bf16x8*)(lds + AT_K + (BUF) * AT_KB + kst0) = K0; *(LAS bf16x8*)(lds + AT_K + (BUF) * AT_KB + kst1) = K1; \
;         *(LAS bf16x8*)(lds + AT_V + (BUF) * AT_VB + vst0) = V0; *(LAS bf16x8*)(lds + AT_V + (BUF) * AT_VB + vst1) = V1; } while (0)
; template <int VAR>
; __device__ __forceinline__ void attn_unit(const Args& a, int l, int b, int h, int qrow0  , bool ctxu, const bf16* Z, bf16* Y, LAS unsigned char* lds) {
;     ...
;     f32x16 negm = f32x16{}, o0 = f32x16{}, o1 = f32x16{}, lacc = f32x16{};
;     float m = 0.f;
;     bf16x8 ka0, ka1, va0, va1, kb0, kb1, vb0_, vb1_;
;     ...
;     AT_LOAD(ka0, ka1, va0, va1, 0); AT_LOAD(kb0, kb1, vb0_, vb1_, 1); AT_STORE(ka0, ka1, va0, va1, 0);
;     const LAS unsigned char* Kb0 = lds + AT_K + comp * 64;
;     for (int t = 0; t < NT; t += 2) {
;         __syncthreads();
;         if (t + 2 < NT) AT_LOAD(ka0, ka1, va0, va1, t + 2);
;         attn_tile(Kb0, vb0, q0, q1, negm, m, o0, o1, lacc, t == 0, wsf, r32, hi);
.LBB0_431:
	v_mov_b32_e32 v79, 0
	v_readfirstlane_b32 s36, v230
	v_readfirstlane_b32 s37, v231
	s_mov_b32 s94, 1
	s_mov_b32 s95, 1
	s_mov_b32 s33, 0
	s_lshr_b32 s50, s29, 6
	s_lshl_b32 s51, s50, 10
	s_lshl_b32 s93, s50, 8
	s_lshl_b32 s50, s50, 3
	v_lshrrev_b32_e32 v132, 3, v227
	v_add_u32_e32 v132, s50, v132
	v_bfe_u32 v133, v132, 1, 3
	v_and_b32_e32 v134, 7, v227
	v_xor_b32_e32 v134, v134, v133
	v_lshlrev_b32_e32 v132, 7, v132
	v_lshl_or_b32 v158, v134, 4, v132
	v_add_u32_e32 v159, 0x2000, v158
	v_bfe_u32 v132, v227, 2, 3
	v_add_u32_e32 v132, s50, v132
	v_lshrrev_b32_e32 v133, 5, v227
	v_and_b32_e32 v134, 3, v227
	v_lshlrev_b32_e32 v133, 6, v133
	v_lshl_or_b32 v133, v134, 4, v133
	v_lshl_or_b32 v160, v132, 7, v133
	v_add_u32_e32 v161, 0x2000, v160
	s_lshl_b32 s50, s8, 2
	v_add_u32_e32 v132, s50, v248
	v_bfe_u32 v133, v247, 1, 3
	v_xor_b32_e32 v132, v132, v133
	v_lshlrev_b32_e32 v133, 7, v247
	v_lshl_or_b32 v144, v132, 4, v133
	v_xor_b32_e32 v145, 32, v144
	v_add_u32_e32 v146, 0x3000, v249
	s_add_u32 s93, s93, 0x19800
	v_lshlrev_b32_e32 v132, 2, v247
	v_add_u32_e32 v148, s93, v132
	v_lshlrev_b32_e32 v132, 4, v248
	v_add_u32_e32 v147, s93, v132
	v_mov_b32_e32 v80, 0
	v_mov_b32_e32 v200, 0
	v_mov_b32_e32 v81, 0
	v_mov_b32_e32 v201, 0
	v_mov_b32_e32 v82, 0
	v_mov_b32_e32 v202, 0
	v_mov_b32_e32 v83, 0
	v_mov_b32_e32 v203, 0
	v_mov_b32_e32 v84, 0
	v_mov_b32_e32 v204, 0
	v_mov_b32_e32 v85, 0
	v_mov_b32_e32 v205, 0
	v_mov_b32_e32 v86, 0
	v_mov_b32_e32 v206, 0
	v_mov_b32_e32 v87, 0
	v_mov_b32_e32 v207, 0
	v_mov_b32_e32 v88, 0
	v_mov_b32_e32 v208, 0
	v_mov_b32_e32 v89, 0
	v_mov_b32_e32 v209, 0
	v_mov_b32_e32 v90, 0
	v_mov_b32_e32 v210, 0
	v_mov_b32_e32 v91, 0
	v_mov_b32_e32 v211, 0
	v_mov_b32_e32 v92, 0
	v_mov_b32_e32 v212, 0
	v_mov_b32_e32 v93, 0
	v_mov_b32_e32 v213, 0
	v_mov_b32_e32 v94, 0
	v_mov_b32_e32 v214, 0
	v_mov_b32_e32 v95, 0
	v_mov_b32_e32 v215, 0
	v_mov_b32_e32 v128, 0
	v_mov_b32_e32 v129, 0
	v_mov_b32_e32 v130, 0
	v_mov_b32_e32 v131, 0
	v_mov_b32_e32 v149, 0
	s_sub_u32 s36, s36, s51
	s_subb_u32 s37, s37, 0
	s_add_u32 s48, s36, 0x1d200000
	s_addc_u32 s49, s37, 0
	s_add_u32 s36, s36, 0x1c000000
	s_addc_u32 s37, s37, 0
	s_cmp_eq_u32 s8, 1
	s_cbranch_scc0 .Lat_noprio
	s_setprio 1
.Lat_noprio:
	s_waitcnt lgkmcnt(0)
	s_add_u32 m0, s51, 0x0
	s_nop 0
	global_load_lds_dwordx4 v158, s[36:37]
	s_add_u32 m0, s51, 0x2000
	s_nop 0
	global_load_lds_dwordx4 v159, s[36:37]
	s_add_u32 m0, s51, 0xc000
	s_nop 0
	global_load_lds_dwordx4 v160, s[48:49]
	s_add_u32 m0, s51, 0xe000
	s_nop 0
	global_load_lds_dwordx4 v161, s[48:49]
	s_add_u32 s36, s36, 0x4000
	s_addc_u32 s37, s37, 0
	s_add_u32 s48, s48, 0x4000
	s_addc_u32 s49, s49, 0
	s_add_u32 m0, s51, 0x4000
	s_nop 0
	global_load_lds_dwordx4 v158, s[36:37]
	s_add_u32 m0, s51, 0x6000
	s_nop 0
	global_load_lds_dwordx4 v159, s[36:37]
	s_add_u32 m0, s51, 0x10000
	s_nop 0
	global_load_lds_dwordx4 v160, s[48:49]
	s_add_u32 m0, s51, 0x12000
	s_nop 0
	global_load_lds_dwordx4 v161, s[48:49]
	s_add_u32 s36, s36, 0x4000
	s_addc_u32 s37, s37, 0
	s_add_u32 s48, s48, 0x4000
	s_addc_u32 s49, s49, 0
	s_waitcnt vmcnt(4)
	s_barrier
	s_add_u32 m0, s51, 0x8000
	s_nop 0
	global_load_lds_dwordx4 v158, s[36:37]
	s_add_u32 m0, s51, 0xa000
	s_nop 0
	global_load_lds_dwordx4 v159, s[36:37]
	s_add_u32 m0, s51, 0x14000
	s_nop 0
	global_load_lds_dwordx4 v160, s[48:49]
	s_add_u32 m0, s51, 0x16000
	s_nop 0
	global_load_lds_dwordx4 v161, s[48:49]
	s_add_u32 s36, s36, 0x4000
	s_addc_u32 s37, s37, 0
	s_add_u32 s48, s48, 0x4000
	s_addc_u32 s49, s49, 0
	ds_read_b128 v[48:51], v144 offset:0
	ds_read_b128 v[52:55], v145 offset:0
	ds_read_b128 v[56:59], v144 offset:4096
	ds_read_b128 v[60:63], v145 offset:4096
.Lat_loop:
	s_waitcnt lgkmcnt(0)
	v_mfma_f32_32x32x16_bf16 v[96:111], v[48:51], v[136:139], v[32:47]
	ds_read_b64_tr_b16 v[168:169], v146 offset:0
	ds_read_b64_tr_b16 v[170:171], v146 offset:1024
	ds_read_b64_tr_b16 v[172:173], v146 offset:512
	ds_read_b64_tr_b16 v[174:175], v146 offset:1536
	v_mfma_f32_32x32x16_bf16 v[96:111], v[52:55], v[140:143], v[96:111]
	ds_read_b64_tr_b16 v[176:177], v146 offset:2048
	ds_read_b64_tr_b16 v[178:179], v146 offset:3072
	ds_read_b64_tr_b16 v[180:181], v146 offset:2560
	ds_read_b64_tr_b16 v[182:183], v146 offset:3584
	v_mfma_f32_32x32x16_bf16 v[112:127], v[56:59], v[136:139], v[32:47]
	ds_read_b64_tr_b16 v[184:185], v146 offset:4096
	ds_read_b64_tr_b16 v[186:187], v146 offset:5120
	ds_read_b64_tr_b16 v[188:189], v146 offset:4608
	ds_read_b64_tr_b16 v[190:191], v146 offset:5632
	v_mfma_f32_32x32x16_bf16 v[112:127], v[60:63], v[140:143], v[112:127]
	ds_read_b64_tr_b16 v[192:193], v146 offset:6144
	ds_read_b64_tr_b16 v[194:195], v146 offset:7168
	ds_read_b64_tr_b16 v[196:197], v146 offset:6656
	ds_read_b64_tr_b16 v[198:199], v146 offset:7680
	v_max3_f32 v132, v96, v97, v98
	v_max3_f32 v133, v99, v100, v101
	v_max3_f32 v132, v132, v102, v103
	v_max3_f32 v133, v133, v104, v105
	v_max3_f32 v132, v132, v106, v107
	v_max3_f32 v133, v133, v108, v109
	v_max3_f32 v132, v132, v110, v111
	s_nop 1
	v_max3_f32 v133, v133, v112, v113
	v_max3_f32 v132, v132, v114, v115
	v_max3_f32 v133, v133, v116, v117
	v_max3_f32 v132, v132, v118, v119
	v_max3_f32 v133, v133, v120, v121
	v_max3_f32 v132, v132, v122, v123
	v_max3_f32 v133, v133, v124, v125
	v_max3_f32 v132, v132, v126, v127
	v_max_f32_e32 v132, v132, v133
	v_mov_b32_e32 v133, v132
	s_nop 1
	v_permlane32_swap_b32_e32 v132, v133
	v_max_f32_e32 v132, v132, v133
	s_cmp_lg_u32 s94, 0
	s_cbranch_scc1 .Lat_rareg0a
	v_cmp_lt_f32_e32 vcc, s4, v132
	s_cbranch_vccnz .Lat_rareg0a
.Lat_backg0a:
	v_exp_f32_e32 v96, v96
	v_exp_f32_e32 v97, v97
	v_exp_f32_e32 v98, v98
	v_exp_f32_e32 v99, v99
	v_exp_f32_e32 v100, v100
	v_exp_f32_e32 v101, v101
	v_exp_f32_e32 v102, v102
	v_exp_f32_e32 v103, v103
	v_cvt_pk_bf16_f32 v162, v96, v97
	v_cvt_pk_bf16_f32 v163, v98, v99
	v_cvt_pk_bf16_f32 v164, v100, v101
	v_cvt_pk_bf16_f32 v165, v102, v103
	v_pk_add_f32 v[128:129], v[128:129], v[96:97]
	v_pk_add_f32 v[128:129], v[128:129], v[98:99]
	v_pk_add_f32 v[128:129], v[128:129], v[100:101]
	v_pk_add_f32 v[128:129], v[128:129], v[102:103]
	s_waitcnt lgkmcnt(12)
	v_mfma_f32_32x32x16_bf16 v[0:15], v[162:165], v[168:171], v[0:15]
	v_exp_f32_e32 v104, v104
	v_exp_f32_e32 v105, v105
	v_exp_f32_e32 v106, v106
	v_exp_f32_e32 v107, v107
	v_mfma_f32_32x32x16_bf16 v[16:31], v[162:165], v[172:175], v[16:31]
	v_exp_f32_e32 v108, v108
	v_exp_f32_e32 v109, v109
	v_exp_f32_e32 v110, v110
	v_exp_f32_e32 v111, v111
	v_cvt_pk_bf16_f32 v162, v104, v105
	v_cvt_pk_bf16_f32 v163, v106, v107
	v_cvt_pk_bf16_f32 v164, v108, v109
	v_cvt_pk_bf16_f32 v165, v110, v111
	v_pk_add_f32 v[128:129], v[128:129], v[104:105]
	v_pk_add_f32 v[128:129], v[128:129], v[106:107]
	v_pk_add_f32 v[128:129], v[128:129], v[108:109]
	v_pk_add_f32 v[128:129], v[128:129], v[110:111]
	s_waitcnt lgkmcnt(8)
	v_mfma_f32_32x32x16_bf16 v[0:15], v[162:165], v[176:179], v[0:15]
	v_exp_f32_e32 v112, v112
	v_exp_f32_e32 v113, v113
	v_exp_f32_e32 v114, v114
	v_exp_f32_e32 v115, v115
	v_mfma_f32_32x32x16_bf16 v[16:31], v[162:165], v[180:183], v[16:31]
	v_mfma_f32_32x32x16_bf16 v[96:111], v[48:51], v[150:153], v[64:79]
	v_exp_f32_e32 v116, v116
	v_exp_f32_e32 v117, v117
	v_exp_f32_e32 v118, v118
	v_exp_f32_e32 v119, v119
	v_mfma_f32_32x32x16_bf16 v[96:111], v[52:55], v[154:157], v[96:111]
	v_cvt_pk_bf16_f32 v162, v112, v113
	v_cvt_pk_bf16_f32 v163, v114, v115
	v_cvt_pk_bf16_f32 v164, v116, v117
	v_cvt_pk_bf16_f32 v165, v118, v119
	v_pk_add_f32 v[128:129], v[128:129], v[112:113]
	v_pk_add_f32 v[128:129], v[128:129], v[114:115]
	v_pk_add_f32 v[128:129], v[128:129], v[116:117]
	v_pk_add_f32 v[128:129], v[128:129], v[118:119]
	s_waitcnt lgkmcnt(4)
	v_mfma_f32_32x32x16_bf16 v[0:15], v[162:165], v[184:187], v[0:15]
	v_exp_f32_e32 v120, v120
	v_exp_f32_e32 v121, v121
	v_exp_f32_e32 v122, v122
	v_exp_f32_e32 v123, v123
	v_mfma_f32_32x32x16_bf16 v[16:31], v[162:165], v[188:191], v[16:31]
	v_exp_f32_e32 v124, v124
	v_exp_f32_e32 v125, v125
	v_exp_f32_e32 v126, v126
	v_exp_f32_e32 v127, v127
	v_cvt_pk_bf16_f32 v162, v120, v121
	v_cvt_pk_bf16_f32 v163, v122, v123
	v_cvt_pk_bf16_f32 v164, v124, v125
	v_cvt_pk_bf16_f32 v165, v126, v127
	v_pk_add_f32 v[128:129], v[128:129], v[120:121]
	v_pk_add_f32 v[128:129], v[128:129], v[122:123]
	v_pk_add_f32 v[128:129], v[128:129], v[124:125]
	v_pk_add_f32 v[128:129], v[128:129], v[126:127]
	s_waitcnt lgkmcnt(0)
	v_mfma_f32_32x32x16_bf16 v[0:15], v[162:165], v[192:195], v[0:15]
	v_mfma_f32_32x32x16_bf16 v[16:31], v[162:165], v[196:199], v[16:31]
	v_mfma_f32_32x32x16_bf16 v[112:127], v[56:59], v[150:153], v[64:79]
	v_mfma_f32_32x32x16_bf16 v[112:127], v[60:63], v[154:157], v[112:127]
	ds_read_b128 v[48:51], v144 offset:8192
	ds_read_b128 v[52:55], v145 offset:8192
	ds_read_b128 v[56:59], v144 offset:12288
	ds_read_b128 v[60:63], v145 offset:12288
	v_max3_f32 v132, v96, v97, v98
	v_max3_f32 v133, v99, v100, v101
	v_max3_f32 v132, v132, v102, v103
	v_max3_f32 v133, v133, v104, v105
	v_max3_f32 v132, v132, v106, v107
	v_max3_f32 v133, v133, v108, v109
	v_max3_f32 v132, v132, v110, v111
	s_nop 1
	v_max3_f32 v133, v133, v112, v113
	v_max3_f32 v132, v132, v114, v115
	v_max3_f32 v133, v133, v116, v117
	v_max3_f32 v132, v132, v118, v119
	v_max3_f32 v133, v133, v120, v121
	v_max3_f32 v132, v132, v122, v123
	v_max3_f32 v133, v133, v124, v125
	v_max3_f32 v132, v132, v126, v127
	v_max_f32_e32 v132, v132, v133
	v_mov_b32_e32 v133, v132
	s_nop 1
	v_permlane32_swap_b32_e32 v132, v133
	v_max_f32_e32 v132, v132, v133
	s_cmp_lg_u32 s95, 0
	s_cbranch_scc1 .Lat_rareg0b
	v_cmp_lt_f32_e32 vcc, s4, v132
	s_cbranch_vccnz .Lat_rareg0b
.Lat_backg0b:
	v_exp_f32_e32 v96, v96
	v_exp_f32_e32 v97, v97
	v_exp_f32_e32 v98, v98
	v_exp_f32_e32 v99, v99
	v_exp_f32_e32 v100, v100
	v_exp_f32_e32 v101, v101
	v_exp_f32_e32 v102, v102
	v_exp_f32_e32 v103, v103
	v_cvt_pk_bf16_f32 v162, v96, v97
	v_cvt_pk_bf16_f32 v163, v98, v99
	v_cvt_pk_bf16_f32 v164, v100, v101
	v_cvt_pk_bf16_f32 v165, v102, v103
	v_pk_add_f32 v[130:131], v[130:131], v[96:97]
	v_pk_add_f32 v[130:131], v[130:131], v[98:99]
	v_pk_add_f32 v[130:131], v[130:131], v[100:101]
	v_pk_add_f32 v[130:131], v[130:131], v[102:103]
	v_mfma_f32_32x32x16_bf16 v[80:95], v[162:165], v[168:171], v[80:95]
	v_exp_f32_e32 v104, v104
	v_exp_f32_e32 v105, v105
	v_exp_f32_e32 v106, v106
	v_exp_f32_e32 v107, v107
	v_mfma_f32_32x32x16_bf16 v[200:215], v[162:165], v[172:175], v[200:215]
	v_exp_f32_e32 v108, v108
	v_exp_f32_e32 v109, v109
	v_exp_f32_e32 v110, v110
	v_exp_f32_e32 v111, v111
	v_cvt_pk_bf16_f32 v162, v104, v105
	v_cvt_pk_bf16_f32 v163, v106, v107
	v_cvt_pk_bf16_f32 v164, v108, v109
	v_cvt_pk_bf16_f32 v165, v110, v111
	v_pk_add_f32 v[130:131], v[130:131], v[104:105]
	v_pk_add_f32 v[130:131], v[130:131], v[106:107]
	v_pk_add_f32 v[130:131], v[130:131], v[108:109]
	v_pk_add_f32 v[130:131], v[130:131], v[110:111]
	v_mfma_f32_32x32x16_bf16 v[80:95], v[162:165], v[176:179], v[80:95]
	v_exp_f32_e32 v112, v112
	v_exp_f32_e32 v113, v113
	v_exp_f32_e32 v114, v114
	v_exp_f32_e32 v115, v115
	v_mfma_f32_32x32x16_bf16 v[200:215], v[162:165], v[180:183], v[200:215]
	v_exp_f32_e32 v116, v116
	v_exp_f32_e32 v117, v117
	v_exp_f32_e32 v118, v118
	v_exp_f32_e32 v119, v119
	v_cvt_pk_bf16_f32 v162, v112, v113
	v_cvt_pk_bf16_f32 v163, v114, v115
	v_cvt_pk_bf16_f32 v164, v116, v117
	v_cvt_pk_bf16_f32 v165, v118, v119
	v_pk_add_f32 v[130:131], v[130:131], v[112:113]
	v_pk_add_f32 v[130:131], v[130:131], v[114:115]
	v_pk_add_f32 v[130:131], v[130:131], v[116:117]
	v_pk_add_f32 v[130:131], v[130:131], v[118:119]
	v_mfma_f32_32x32x16_bf16 v[80:95], v[162:165], v[184:187], v[80:95]
	v_exp_f32_e32 v120, v120
	v_exp_f32_e32 v121, v121
	v_exp_f32_e32 v122, v122
	v_exp_f32_e32 v123, v123
	v_mfma_f32_32x32x16_bf16 v[200:215], v[162:165], v[188:191], v[200:215]
	v_exp_f32_e32 v124, v124
	v_exp_f32_e32 v125, v125
	v_exp_f32_e32 v126, v126
	v_exp_f32_e32 v127, v127
	v_cvt_pk_bf16_f32 v162, v120, v121
	v_cvt_pk_bf16_f32 v163, v122, v123
	v_cvt_pk_bf16_f32 v164, v124, v125
	v_cvt_pk_bf16_f32 v165, v126, v127
	v_pk_add_f32 v[130:131], v[130:131], v[120:121]
	v_pk_add_f32 v[130:131], v[130:131], v[122:123]
	v_pk_add_f32 v[130:131], v[130:131], v[124:125]
	v_pk_add_f32 v[130:131], v[130:131], v[126:127]
	v_mfma_f32_32x32x16_bf16 v[80:95], v[162:165], v[192:195], v[80:95]
	v_mfma_f32_32x32x16_bf16 v[200:215], v[162:165], v[196:199], v[200:215]
	s_waitcnt lgkmcnt(0)
	v_mfma_f32_32x32x16_bf16 v[96:111], v[48:51], v[136:139], v[32:47]
	ds_read_b64_tr_b16 v[168:169], v146 offset:8192
	ds_read_b64_tr_b16 v[170:171], v146 offset:9216
	ds_read_b64_tr_b16 v[172:173], v146 offset:8704
	ds_read_b64_tr_b16 v[174:175], v146 offset:9728
	v_mfma_f32_32x32x16_bf16 v[96:111], v[52:55], v[140:143], v[96:111]
	ds_read_b64_tr_b16 v[176:177], v146 offset:10240
	ds_read_b64_tr_b16 v[178:179], v146 offset:11264
	ds_read_b64_tr_b16 v[180:181], v146 offset:10752
	ds_read_b64_tr_b16 v[182:183], v146 offset:11776
	v_mfma_f32_32x32x16_bf16 v[112:127], v[56:59], v[136:139], v[32:47]
	ds_read_b64_tr_b16 v[184:185], v146 offset:12288
	ds_read_b64_tr_b16 v[186:187], v146 offset:13312
	ds_read_b64_tr_b16 v[188:189], v146 offset:12800
	ds_read_b64_tr_b16 v[190:191], v146 offset:13824
	v_mfma_f32_32x32x16_bf16 v[112:127], v[60:63], v[140:143], v[112:127]
	ds_read_b64_tr_b16 v[192:193], v146 offset:14336
	ds_read_b64_tr_b16 v[194:195], v146 offset:15360
	ds_read_b64_tr_b16 v[196:197], v146 offset:14848
	ds_read_b64_tr_b16 v[198:199], v146 offset:15872
	v_max3_f32 v132, v96, v97, v98
	v_max3_f32 v133, v99, v100, v101
	v_max3_f32 v132, v132, v102, v103
	v_max3_f32 v133, v133, v104, v105
	v_max3_f32 v132, v132, v106, v107
	v_max3_f32 v133, v133, v108, v109
	v_max3_f32 v132, v132, v110, v111
	s_nop 1
	v_max3_f32 v133, v133, v112, v113
	v_max3_f32 v132, v132, v114, v115
	v_max3_f32 v133, v133, v116, v117
	v_max3_f32 v132, v132, v118, v119
	v_max3_f32 v133, v133, v120, v121
	v_max3_f32 v132, v132, v122, v123
	v_max3_f32 v133, v133, v124, v125
	v_max3_f32 v132, v132, v126, v127
	v_max_f32_e32 v132, v132, v133
	v_mov_b32_e32 v133, v132
	s_nop 1
	v_permlane32_swap_b32_e32 v132, v133
	v_max_f32_e32 v132, v132, v133
	v_cmp_lt_f32_e32 vcc, s4, v132
	s_cbranch_vccnz .Lat_rareg1a
.Lat_backg1a:
	v_exp_f32_e32 v96, v96
	v_exp_f32_e32 v97, v97
	v_exp_f32_e32 v98, v98
	v_exp_f32_e32 v99, v99
	v_exp_f32_e32 v100, v100
	v_exp_f32_e32 v101, v101
	v_exp_f32_e32 v102, v102
	v_exp_f32_e32 v103, v103
	v_cvt_pk_bf16_f32 v162, v96, v97
	v_cvt_pk_bf16_f32 v163, v98, v99
	v_cvt_pk_bf16_f32 v164, v100, v101
	v_cvt_pk_bf16_f32 v165, v102, v103
	v_pk_add_f32 v[128:129], v[128:129], v[96:97]
	v_pk_add_f32 v[128:129], v[128:129], v[98:99]
	v_pk_add_f32 v[128:129], v[128:129], v[100:101]
	v_pk_add_f32 v[128:129], v[128:129], v[102:103]
	s_waitcnt lgkmcnt(12)
	v_mfma_f32_32x32x16_bf16 v[0:15], v[162:165], v[168:171], v[0:15]
	v_exp_f32_e32 v104, v104
	v_exp_f32_e32 v105, v105
	v_exp_f32_e32 v106, v106
	v_exp_f32_e32 v107, v107
	v_mfma_f32_32x32x16_bf16 v[16:31], v[162:165], v[172:175], v[16:31]
	v_exp_f32_e32 v108, v108
	v_exp_f32_e32 v109, v109
	v_exp_f32_e32 v110, v110
	v_exp_f32_e32 v111, v111
	v_cvt_pk_bf16_f32 v162, v104, v105
	v_cvt_pk_bf16_f32 v163, v106, v107
	v_cvt_pk_bf16_f32 v164, v108, v109
	v_cvt_pk_bf16_f32 v165, v110, v111
	v_pk_add_f32 v[128:129], v[128:129], v[104:105]
	v_pk_add_f32 v[128:129], v[128:129], v[106:107]
	v_pk_add_f32 v[128:129], v[128:129], v[108:109]
	v_pk_add_f32 v[128:129], v[128:129], v[110:111]
	s_waitcnt lgkmcnt(8)
	v_mfma_f32_32x32x16_bf16 v[0:15], v[162:165], v[176:179], v[0:15]
	v_exp_f32_e32 v112, v112
	v_exp_f32_e32 v113, v113
	v_exp_f32_e32 v114, v114
	v_exp_f32_e32 v115, v115
	v_mfma_f32_32x32x16_bf16 v[16:31], v[162:165], v[180:183], v[16:31]
	v_mfma_f32_32x32x16_bf16 v[96:111], v[48:51], v[150:153], v[64:79]
	v_exp_f32_e32 v116, v116
	v_exp_f32_e32 v117, v117
	v_exp_f32_e32 v118, v118
	v_exp_f32_e32 v119, v119
	v_mfma_f32_32x32x16_bf16 v[96:111], v[52:55], v[154:157], v[96:111]
	v_cvt_pk_bf16_f32 v162, v112, v113
	v_cvt_pk_bf16_f32 v163, v114, v115
	v_cvt_pk_bf16_f32 v164, v116, v117
	v_cvt_pk_bf16_f32 v165, v118, v119
	v_pk_add_f32 v[128:129], v[128:129], v[112:113]
	v_pk_add_f32 v[128:129], v[128:129], v[114:115]
	v_pk_add_f32 v[128:129], v[128:129], v[116:117]
	v_pk_add_f32 v[128:129], v[128:129], v[118:119]
	s_waitcnt lgkmcnt(4)
	v_mfma_f32_32x32x16_bf16 v[0:15], v[162:165], v[184:187], v[0:15]
	v_exp_f32_e32 v120, v120
	v_exp_f32_e32 v121, v121
	v_exp_f32_e32 v122, v122
	v_exp_f32_e32 v123, v123
	v_mfma_f32_32x32x16_bf16 v[16:31], v[162:165], v[188:191], v[16:31]
	v_exp_f32_e32 v124, v124
	v_exp_f32_e32 v125, v125
	v_exp_f32_e32 v126, v126
	v_exp_f32_e32 v127, v127
	v_cvt_pk_bf16_f32 v162, v120, v121
	v_cvt_pk_bf16_f32 v163, v122, v123
	v_cvt_pk_bf16_f32 v164, v124, v125
	v_cvt_pk_bf16_f32 v165, v126, v127
	v_pk_add_f32 v[128:129], v[128:129], v[120:121]
	v_pk_add_f32 v[128:129], v[128:129], v[122:123]
	v_pk_add_f32 v[128:129], v[128:129], v[124:125]
	v_pk_add_f32 v[128:129], v[128:129], v[126:127]
	s_waitcnt lgkmcnt(0)
	v_mfma_f32_32x32x16_bf16 v[0:15], v[162:165], v[192:195], v[0:15]
	v_mfma_f32_32x32x16_bf16 v[16:31], v[162:165], v[196:199], v[16:31]
	v_mfma_f32_32x32x16_bf16 v[112:127], v[56:59], v[150:153], v[64:79]
	v_mfma_f32_32x32x16_bf16 v[112:127], v[60:63], v[154:157], v[112:127]
	v_max3_f32 v132, v96, v97, v98
	v_max3_f32 v133, v99, v100, v101
	v_max3_f32 v132, v132, v102, v103
	v_max3_f32 v133, v133, v104, v105
	v_max3_f32 v132, v132, v106, v107
	v_max3_f32 v133, v133, v108, v109
	v_max3_f32 v132, v132, v110, v111
	s_nop 5
	v_max3_f32 v133, v133, v112, v113
	v_max3_f32 v132, v132, v114, v115
	v_max3_f32 v133, v133, v116, v117
	v_max3_f32 v132, v132, v118, v119
	v_max3_f32 v133, v133, v120, v121
	v_max3_f32 v132, v132, v122, v123
	v_max3_f32 v133, v133, v124, v125
	v_max3_f32 v132, v132, v126, v127
	v_max_f32_e32 v132, v132, v133
	v_mov_b32_e32 v133, v132
	s_nop 1
	v_permlane32_swap_b32_e32 v132, v133
	v_max_f32_e32 v132, v132, v133
	v_cmp_lt_f32_e32 vcc, s4, v132
	s_cbranch_vccnz .Lat_rareg1b
; #define AT_LOAD(K0, K1, V0, V1, T) do { const size_t e_ = (size_t)(128 * (T) + sr) * 64 + sc; \
;         K0 = *(const bf16x8*)(kcp + e_); V0 = *(const bf16x8*)(vcp + e_); K1 = *(const bf16x8*)(kcp + e_ + 64 * 64); V1 = *(const bf16x8*)(vcp + e_ + 64 * 64); } while (0)
; #define AT_STORE(K0, K1, V0, V1, BUF) do { *(LAS bf16x8*)(lds + AT_K + (BUF) * AT_KB + kst0) = K0; *(LAS bf16x8*)(lds + AT_K + (BUF) * AT_KB + kst1) = K1; \
;         *(LAS bf16x8*)(lds + AT_V + (BUF) * AT_VB + vst0) = V0; *(LAS bf16x8*)(lds + AT_V + (BUF) * AT_VB + vst1) = V1; } while (0)
; template <int VAR>
; __device__ __forceinline__ void attn_unit(const Args& a, int l, int b, int h, int qrow0  , bool ctxu, const bf16* Z, bf16* Y, LAS unsigned char* lds) {
;     ...
;     for (int t = 0; t < NT; t += 2) {
;         __syncthreads();
;         if (t + 2 < NT) AT_LOAD(ka0, ka1, va0, va1, t + 2);
;         attn_tile(Kb0, vb0, q0, q1, negm, m, o0, o1, lacc, t == 0, wsf, r32, hi);
;         AT_STORE(kb0, kb1, vb0_, vb1_, 1);
;         __syncthreads();
;         if (t + 3 < NT) AT_LOAD(kb0, kb1, vb0_, vb1_, t + 3);
;         attn_tile(Kb0 + AT_KB, vb0 + AT_VB, q0, q1, negm, m, o0, o1, lacc, false, wsf, r32, hi);
;         if (t + 2 < NT) AT_STORE(ka0, ka1, va0, va1, 0);
.Lat_backg1b:
	v_exp_f32_e32 v96, v96
	v_exp_f32_e32 v97, v97
	v_exp_f32_e32 v98, v98
	v_exp_f32_e32 v99, v99
	v_exp_f32_e32 v100, v100
	v_exp_f32_e32 v101, v101
	v_exp_f32_e32 v102, v102
	v_exp_f32_e32 v103, v103
	v_cvt_pk_bf16_f32 v162, v96, v97
	v_cvt_pk_bf16_f32 v163, v98, v99
	v_cvt_pk_bf16_f32 v164, v100, v101
	v_cvt_pk_bf16_f32 v165, v102, v103
	v_pk_add_f32 v[130:131], v[130:131], v[96:97]
	v_pk_add_f32 v[130:131], v[130:131], v[98:99]
	v_pk_add_f32 v[130:131], v[130:131], v[100:101]
	v_pk_add_f32 v[130:131], v[130:131], v[102:103]
	v_mfma_f32_32x32x16_bf16 v[80:95], v[162:165], v[168:171], v[80:95]
	v_exp_f32_e32 v104, v104
	v_exp_f32_e32 v105, v105
	v_exp_f32_e32 v106, v106
	v_exp_f32_e32 v107, v107
	v_mfma_f32_32x32x16_bf16 v[200:215], v[162:165], v[172:175], v[200:215]
	v_exp_f32_e32 v108, v108
	v_exp_f32_e32 v109, v109
	v_exp_f32_e32 v110, v110
	v_exp_f32_e32 v111, v111
	v_cvt_pk_bf16_f32 v162, v104, v105
	v_cvt_pk_bf16_f32 v163, v106, v107
	v_cvt_pk_bf16_f32 v164, v108, v109
	v_cvt_pk_bf16_f32 v165, v110, v111
	v_pk_add_f32 v[130:131], v[130:131], v[104:105]
	v_pk_add_f32 v[130:131], v[130:131], v[106:107]
	v_pk_add_f32 v[130:131], v[130:131], v[108:109]
	v_pk_add_f32 v[130:131], v[130:131], v[110:111]
	v_mfma_f32_32x32x16_bf16 v[80:95], v[162:165], v[176:179], v[80:95]
	v_exp_f32_e32 v112, v112
	v_exp_f32_e32 v113, v113
	v_exp_f32_e32 v114, v114
	v_exp_f32_e32 v115, v115
	v_mfma_f32_32x32x16_bf16 v[200:215], v[162:165], v[180:183], v[200:215]
	v_exp_f32_e32 v116, v116
	v_exp_f32_e32 v117, v117
	v_exp_f32_e32 v118, v118
	v_exp_f32_e32 v119, v119
	v_cvt_pk_bf16_f32 v162, v112, v113
	v_cvt_pk_bf16_f32 v163, v114, v115
	v_cvt_pk_bf16_f32 v164, v116, v117
	v_cvt_pk_bf16_f32 v165, v118, v119
	v_pk_add_f32 v[130:131], v[130:131], v[112:113]
	v_pk_add_f32 v[130:131], v[130:131], v[114:115]
	v_pk_add_f32 v[130:131], v[130:131], v[116:117]
	v_pk_add_f32 v[130:131], v[130:131], v[118:119]
	v_mfma_f32_32x32x16_bf16 v[80:95], v[162:165], v[184:187], v[80:95]
	v_exp_f32_e32 v120, v120
	v_exp_f32_e32 v121, v121
	v_exp_f32_e32 v122, v122
	v_exp_f32_e32 v123, v123
	v_mfma_f32_32x32x16_bf16 v[200:215], v[162:165], v[188:191], v[200:215]
	v_exp_f32_e32 v124, v124
	v_exp_f32_e32 v125, v125
	v_exp_f32_e32 v126, v126
	v_exp_f32_e32 v127, v127
	v_cvt_pk_bf16_f32 v162, v120, v121
	v_cvt_pk_bf16_f32 v163, v122, v123
	v_cvt_pk_bf16_f32 v164, v124, v125
	v_cvt_pk_bf16_f32 v165, v126, v127
	v_pk_add_f32 v[130:131], v[130:131], v[120:121]
	v_pk_add_f32 v[130:131], v[130:131], v[122:123]
	v_pk_add_f32 v[130:131], v[130:131], v[124:125]
	v_pk_add_f32 v[130:131], v[130:131], v[126:127]
	s_waitcnt vmcnt(4)
	s_waitcnt lgkmcnt(0)
	s_barrier
	s_cmp_eq_u32 s33, 21
	s_cbranch_scc1 .Lat_ndg1
	s_add_u32 m0, s51, 0x0
	s_nop 0
	global_load_lds_dwordx4 v158, s[36:37]
	s_add_u32 m0, s51, 0x2000
	s_nop 0
	global_load_lds_dwordx4 v159, s[36:37]
	s_add_u32 m0, s51, 0xc000
	s_nop 0
	global_load_lds_dwordx4 v160, s[48:49]
	s_add_u32 m0, s51, 0xe000
	s_nop 0
	global_load_lds_dwordx4 v161, s[48:49]
	s_add_u32 s36, s36, 0x4000
	s_addc_u32 s37, s37, 0
	s_add_u32 s48, s48, 0x4000
	s_addc_u32 s49, s49, 0
.Lat_ndg1:
	ds_read_b128 v[48:51], v144 offset:16384
	ds_read_b128 v[52:55], v145 offset:16384
	ds_read_b128 v[56:59], v144 offset:20480
	ds_read_b128 v[60:63], v145 offset:20480
	v_mfma_f32_32x32x16_bf16 v[80:95], v[162:165], v[192:195], v[80:95]
	v_mfma_f32_32x32x16_bf16 v[200:215], v[162:165], v[196:199], v[200:215]
	s_waitcnt lgkmcnt(0)
	v_mfma_f32_32x32x16_bf16 v[96:111], v[48:51], v[136:139], v[32:47]
	ds_read_b64_tr_b16 v[168:169], v146 offset:16384
	ds_read_b64_tr_b16 v[170:171], v146 offset:17408
	ds_read_b64_tr_b16 v[172:173], v146 offset:16896
	ds_read_b64_tr_b16 v[174:175], v146 offset:17920
	v_mfma_f32_32x32x16_bf16 v[96:111], v[52:55], v[140:143], v[96:111]
	ds_read_b64_tr_b16 v[176:177], v146 offset:18432
	ds_read_b64_tr_b16 v[178:179], v146 offset:19456
	ds_read_b64_tr_b16 v[180:181], v146 offset:18944
	ds_read_b64_tr_b16 v[182:183], v146 offset:19968
	v_mfma_f32_32x32x16_bf16 v[112:127], v[56:59], v[136:139], v[32:47]
	ds_read_b64_tr_b16 v[184:185], v146 offset:20480
	ds_read_b64_tr_b16 v[186:187], v146 offset:21504
	ds_read_b64_tr_b16 v[188:189], v146 offset:20992
	ds_read_b64_tr_b16 v[190:191], v146 offset:22016
	v_mfma_f32_32x32x16_bf16 v[112:127], v[60:63], v[140:143], v[112:127]
	ds_read_b64_tr_b16 v[192:193], v146 offset:22528
	ds_read_b64_tr_b16 v[194:195], v146 offset:23552
	ds_read_b64_tr_b16 v[196:197], v146 offset:23040
	ds_read_b64_tr_b16 v[198:199], v146 offset:24064
	v_max3_f32 v132, v96, v97, v98
	v_max3_f32 v133, v99, v100, v101
	v_max3_f32 v132, v132, v102, v103
	v_max3_f32 v133, v133, v104, v105
	v_max3_f32 v132, v132, v106, v107
	v_max3_f32 v133, v133, v108, v109
	v_max3_f32 v132, v132, v110, v111
	s_nop 1
	v_max3_f32 v133, v133, v112, v113
	v_max3_f32 v132, v132, v114, v115
	v_max3_f32 v133, v133, v116, v117
	v_max3_f32 v132, v132, v118, v119
	v_max3_f32 v133, v133, v120, v121
	v_max3_f32 v132, v132, v122, v123
	v_max3_f32 v133, v133, v124, v125
	v_max3_f32 v132, v132, v126, v127
	v_max_f32_e32 v132, v132, v133
	v_mov_b32_e32 v133, v132
	s_nop 1
	v_permlane32_swap_b32_e32 v132, v133
	v_max_f32_e32 v132, v132, v133
	v_cmp_lt_f32_e32 vcc, s4, v132
	s_cbranch_vccnz .Lat_rareg2a
.Lat_backg2a:
	v_exp_f32_e32 v96, v96
	v_exp_f32_e32 v97, v97
	v_exp_f32_e32 v98, v98
	v_exp_f32_e32 v99, v99
	v_exp_f32_e32 v100, v100
	v_exp_f32_e32 v101, v101
	v_exp_f32_e32 v102, v102
	v_exp_f32_e32 v103, v103
	v_cvt_pk_bf16_f32 v162, v96, v97
	v_cvt_pk_bf16_f32 v163, v98, v99
	v_cvt_pk_bf16_f32 v164, v100, v101
	v_cvt_pk_bf16_f32 v165, v102, v103
	v_pk_add_f32 v[128:129], v[128:129], v[96:97]
	v_pk_add_f32 v[128:129], v[128:129], v[98:99]
	v_pk_add_f32 v[128:129], v[128:129], v[100:101]
	v_pk_add_f32 v[128:129], v[128:129], v[102:103]
	s_waitcnt lgkmcnt(12)
	v_mfma_f32_32x32x16_bf16 v[0:15], v[162:165], v[168:171], v[0:15]
	v_exp_f32_e32 v104, v104
	v_exp_f32_e32 v105, v105
	v_exp_f32_e32 v106, v106
	v_exp_f32_e32 v107, v107
	v_mfma_f32_32x32x16_bf16 v[16:31], v[162:165], v[172:175], v[16:31]
	v_exp_f32_e32 v108, v108
	v_exp_f32_e32 v109, v109
	v_exp_f32_e32 v110, v110
	v_exp_f32_e32 v111, v111
	v_cvt_pk_bf16_f32 v162, v104, v105
	v_cvt_pk_bf16_f32 v163, v106, v107
	v_cvt_pk_bf16_f32 v164, v108, v109
	v_cvt_pk_bf16_f32 v165, v110, v111
	v_pk_add_f32 v[128:129], v[128:129], v[104:105]
	v_pk_add_f32 v[128:129], v[128:129], v[106:107]
	v_pk_add_f32 v[128:129], v[128:129], v[108:109]
	v_pk_add_f32 v[128:129], v[128:129], v[110:111]
	s_waitcnt lgkmcnt(8)
	v_mfma_f32_32x32x16_bf16 v[0:15], v[162:165], v[176:179], v[0:15]
	v_exp_f32_e32 v112, v112
	v_exp_f32_e32 v113, v113
	v_exp_f32_e32 v114, v114
	v_exp_f32_e32 v115, v115
	v_mfma_f32_32x32x16_bf16 v[16:31], v[162:165], v[180:183], v[16:31]
	v_mfma_f32_32x32x16_bf16 v[96:111], v[48:51], v[150:153], v[64:79]
	v_exp_f32_e32 v116, v116
	v_exp_f32_e32 v117, v117
	v_exp_f32_e32 v118, v118
	v_exp_f32_e32 v119, v119
	v_mfma_f32_32x32x16_bf16 v[96:111], v[52:55], v[154:157], v[96:111]
	v_cvt_pk_bf16_f32 v162, v112, v113
	v_cvt_pk_bf16_f32 v163, v114, v115
	v_cvt_pk_bf16_f32 v164, v116, v117
	v_cvt_pk_bf16_f32 v165, v118, v119
	v_pk_add_f32 v[128:129], v[128:129], v[112:113]
	v_pk_add_f32 v[128:129], v[128:129], v[114:115]
	v_pk_add_f32 v[128:129], v[128:129], v[116:117]
	v_pk_add_f32 v[128:129], v[128:129], v[118:119]
	s_waitcnt lgkmcnt(4)
	v_mfma_f32_32x32x16_bf16 v[0:15], v[162:165], v[184:187], v[0:15]
	v_exp_f32_e32 v120, v120
	v_exp_f32_e32 v121, v121
	v_exp_f32_e32 v122, v122
	v_exp_f32_e32 v123, v123
	v_mfma_f32_32x32x16_bf16 v[16:31], v[162:165], v[188:191], v[16:31]
	v_exp_f32_e32 v124, v124
	v_exp_f32_e32 v125, v125
	v_exp_f32_e32 v126, v126
	v_exp_f32_e32 v127, v127
	v_cvt_pk_bf16_f32 v162, v120, v121
	v_cvt_pk_bf16_f32 v163, v122, v123
	v_cvt_pk_bf16_f32 v164, v124, v125
	v_cvt_pk_bf16_f32 v165, v126, v127
	v_pk_add_f32 v[128:129], v[128:129], v[120:121]
	v_pk_add_f32 v[128:129], v[128:129], v[122:123]
	v_pk_add_f32 v[128:129], v[128:129], v[124:125]
	v_pk_add_f32 v[128:129], v[128:129], v[126:127]
	s_waitcnt lgkmcnt(0)
	v_mfma_f32_32x32x16_bf16 v[0:15], v[162:165], v[192:195], v[0:15]
	v_mfma_f32_32x32x16_bf16 v[16:31], v[162:165], v[196:199], v[16:31]
	v_mfma_f32_32x32x16_bf16 v[112:127], v[56:59], v[150:153], v[64:79]
	v_mfma_f32_32x32x16_bf16 v[112:127], v[60:63], v[154:157], v[112:127]
	ds_read_b128 v[48:51], v144 offset:24576
	ds_read_b128 v[52:55], v145 offset:24576
	ds_read_b128 v[56:59], v144 offset:28672
	ds_read_b128 v[60:63], v145 offset:28672
	v_max3_f32 v132, v96, v97, v98
	v_max3_f32 v133, v99, v100, v101
	v_max3_f32 v132, v132, v102, v103
	v_max3_f32 v133, v133, v104, v105
	v_max3_f32 v132, v132, v106, v107
	v_max3_f32 v133, v133, v108, v109
	v_max3_f32 v132, v132, v110, v111
	s_nop 1
	v_max3_f32 v133, v133, v112, v113
	v_max3_f32 v132, v132, v114, v115
	v_max3_f32 v133, v133, v116, v117
	v_max3_f32 v132, v132, v118, v119
	v_max3_f32 v133, v133, v120, v121
	v_max3_f32 v132, v132, v122, v123
	v_max3_f32 v133, v133, v124, v125
	v_max3_f32 v132, v132, v126, v127
	v_max_f32_e32 v132, v132, v133
	v_mov_b32_e32 v133, v132
	s_nop 1
	v_permlane32_swap_b32_e32 v132, v133
	v_max_f32_e32 v132, v132, v133
	v_cmp_lt_f32_e32 vcc, s4, v132
	s_cbranch_vccnz .Lat_rareg2b
.Lat_backg2b:
	v_exp_f32_e32 v96, v96
	v_exp_f32_e32 v97, v97
	v_exp_f32_e32 v98, v98
	v_exp_f32_e32 v99, v99
	v_exp_f32_e32 v100, v100
	v_exp_f32_e32 v101, v101
	v_exp_f32_e32 v102, v102
	v_exp_f32_e32 v103, v103
	v_cvt_pk_bf16_f32 v162, v96, v97
	v_cvt_pk_bf16_f32 v163, v98, v99
	v_cvt_pk_bf16_f32 v164, v100, v101
	v_cvt_pk_bf16_f32 v165, v102, v103
	v_pk_add_f32 v[130:131], v[130:131], v[96:97]
	v_pk_add_f32 v[130:131], v[130:131], v[98:99]
	v_pk_add_f32 v[130:131], v[130:131], v[100:101]
	v_pk_add_f32 v[130:131], v[130:131], v[102:103]
	v_mfma_f32_32x32x16_bf16 v[80:95], v[162:165], v[168:171], v[80:95]
	v_exp_f32_e32 v104, v104
	v_exp_f32_e32 v105, v105
	v_exp_f32_e32 v106, v106
	v_exp_f32_e32 v107, v107
	v_mfma_f32_32x32x16_bf16 v[200:215], v[162:165], v[172:175], v[200:215]
	v_exp_f32_e32 v108, v108
	v_exp_f32_e32 v109, v109
	v_exp_f32_e32 v110, v110
	v_exp_f32_e32 v111, v111
	v_cvt_pk_bf16_f32 v162, v104, v105
	v_cvt_pk_bf16_f32 v163, v106, v107
	v_cvt_pk_bf16_f32 v164, v108, v109
	v_cvt_pk_bf16_f32 v165, v110, v111
	v_pk_add_f32 v[130:131], v[130:131], v[104:105]
	v_pk_add_f32 v[130:131], v[130:131], v[106:107]
	v_pk_add_f32 v[130:131], v[130:131], v[108:109]
	v_pk_add_f32 v[130:131], v[130:131], v[110:111]
	v_mfma_f32_32x32x16_bf16 v[80:95], v[162:165], v[176:179], v[80:95]
	v_exp_f32_e32 v112, v112
	v_exp_f32_e32 v113, v113
	v_exp_f32_e32 v114, v114
	v_exp_f32_e32 v115, v115
	v_mfma_f32_32x32x16_bf16 v[200:215], v[162:165], v[180:183], v[200:215]
	v_exp_f32_e32 v116, v116
	v_exp_f32_e32 v117, v117
	v_exp_f32_e32 v118, v118
	v_exp_f32_e32 v119, v119
	v_cvt_pk_bf16_f32 v162, v112, v113
	v_cvt_pk_bf16_f32 v163, v114, v115
	v_cvt_pk_bf16_f32 v164, v116, v117
	v_cvt_pk_bf16_f32 v165, v118, v119
	v_pk_add_f32 v[130:131], v[130:131], v[112:113]
	v_pk_add_f32 v[130:131], v[130:131], v[114:115]
	v_pk_add_f32 v[130:131], v[130:131], v[116:117]
	v_pk_add_f32 v[130:131], v[130:131], v[118:119]
	v_mfma_f32_32x32x16_bf16 v[80:95], v[162:165], v[184:187], v[80:95]
	v_exp_f32_e32 v120, v120
	v_exp_f32_e32 v121, v121
	v_exp_f32_e32 v122, v122
	v_exp_f32_e32 v123, v123
	v_mfma_f32_32x32x16_bf16 v[200:215], v[162:165], v[188:191], v[200:215]
	v_exp_f32_e32 v124, v124
	v_exp_f32_e32 v125, v125
	v_exp_f32_e32 v126, v126
	v_exp_f32_e32 v127, v127
	v_cvt_pk_bf16_f32 v162, v120, v121
	v_cvt_pk_bf16_f32 v163, v122, v123
	v_cvt_pk_bf16_f32 v164, v124, v125
	v_cvt_pk_bf16_f32 v165, v126, v127
	v_pk_add_f32 v[130:131], v[130:131], v[120:121]
	v_pk_add_f32 v[130:131], v[130:131], v[122:123]
	v_pk_add_f32 v[130:131], v[130:131], v[124:125]
	v_pk_add_f32 v[130:131], v[130:131], v[126:127]
	v_mfma_f32_32x32x16_bf16 v[80:95], v[162:165], v[192:195], v[80:95]
	v_mfma_f32_32x32x16_bf16 v[200:215], v[162:165], v[196:199], v[200:215]
	s_waitcnt lgkmcnt(0)
	v_mfma_f32_32x32x16_bf16 v[96:111], v[48:51], v[136:139], v[32:47]
	ds_read_b64_tr_b16 v[168:169], v146 offset:24576
	ds_read_b64_tr_b16 v[170:171], v146 offset:25600
	ds_read_b64_tr_b16 v[172:173], v146 offset:25088
	ds_read_b64_tr_b16 v[174:175], v146 offset:26112
	v_mfma_f32_32x32x16_bf16 v[96:111], v[52:55], v[140:143], v[96:111]
	ds_read_b64_tr_b16 v[176:177], v146 offset:26624
	ds_read_b64_tr_b16 v[178:179], v146 offset:27648
	ds_read_b64_tr_b16 v[180:181], v146 offset:27136
	ds_read_b64_tr_b16 v[182:183], v146 offset:28160
	v_mfma_f32_32x32x16_bf16 v[112:127], v[56:59], v[136:139], v[32:47]
	ds_read_b64_tr_b16 v[184:185], v146 offset:28672
	ds_read_b64_tr_b16 v[186:187], v146 offset:29696
	ds_read_b64_tr_b16 v[188:189], v146 offset:29184
	ds_read_b64_tr_b16 v[190:191], v146 offset:30208
	v_mfma_f32_32x32x16_bf16 v[112:127], v[60:63], v[140:143], v[112:127]
	ds_read_b64_tr_b16 v[192:193], v146 offset:30720
	ds_read_b64_tr_b16 v[194:195], v146 offset:31744
	ds_read_b64_tr_b16 v[196:197], v146 offset:31232
	ds_read_b64_tr_b16 v[198:199], v146 offset:32256
	v_max3_f32 v132, v96, v97, v98
	v_max3_f32 v133, v99, v100, v101
	v_max3_f32 v132, v132, v102, v103
	v_max3_f32 v133, v133, v104, v105
	v_max3_f32 v132, v132, v106, v107
	v_max3_f32 v133, v133, v108, v109
	v_max3_f32 v132, v132, v110, v111
	s_nop 1
	v_max3_f32 v133, v133, v112, v113
	v_max3_f32 v132, v132, v114, v115
	v_max3_f32 v133, v133, v116, v117
	v_max3_f32 v132, v132, v118, v119
	v_max3_f32 v133, v133, v120, v121
	v_max3_f32 v132, v132, v122, v123
	v_max3_f32 v133, v133, v124, v125
	v_max3_f32 v132, v132, v126, v127
	v_max_f32_e32 v132, v132, v133
	v_mov_b32_e32 v133, v132
	s_nop 1
	v_permlane32_swap_b32_e32 v132, v133
	v_max_f32_e32 v132, v132, v133
	v_cmp_lt_f32_e32 vcc, s4, v132
	s_cbranch_vccnz .Lat_rareg3a

.Lat_backg3b:
	v_exp_f32_e32 v96, v96
	v_exp_f32_e32 v97, v97
	v_exp_f32_e32 v98, v98
	v_exp_f32_e32 v99, v99
	v_exp_f32_e32 v100, v100
	v_exp_f32_e32 v101, v101
	v_exp_f32_e32 v102, v102
	v_exp_f32_e32 v103, v103
	v_cvt_pk_bf16_f32 v162, v96, v97
	v_cvt_pk_bf16_f32 v163, v98, v99
	v_cvt_pk_bf16_f32 v164, v100, v101
	v_cvt_pk_bf16_f32 v165, v102, v103
	v_pk_add_f32 v[130:131], v[130:131], v[96:97]
	v_pk_add_f32 v[130:131], v[130:131], v[98:99]
	v_pk_add_f32 v[130:131], v[130:131], v[100:101]
	v_pk_add_f32 v[130:131], v[130:131], v[102:103]
	v_mfma_f32_32x32x16_bf16 v[80:95], v[162:165], v[168:171], v[80:95]
	v_exp_f32_e32 v104, v104
	v_exp_f32_e32 v105, v105
	v_exp_f32_e32 v106, v106
	v_exp_f32_e32 v107, v107
	v_mfma_f32_32x32x16_bf16 v[200:215], v[162:165], v[172:175], v[200:215]
	v_exp_f32_e32 v108, v108
	v_exp_f32_e32 v109, v109
	v_exp_f32_e32 v110, v110
	v_exp_f32_e32 v111, v111
	v_cvt_pk_bf16_f32 v162, v104, v105
	v_cvt_pk_bf16_f32 v163, v106, v107
	v_cvt_pk_bf16_f32 v164, v108, v109
	v_cvt_pk_bf16_f32 v165, v110, v111
	v_pk_add_f32 v[130:131], v[130:131], v[104:105]
	v_pk_add_f32 v[130:131], v[130:131], v[106:107]
	v_pk_add_f32 v[130:131], v[130:131], v[108:109]
	v_pk_add_f32 v[130:131], v[130:131], v[110:111]
	v_mfma_f32_32x32x16_bf16 v[80:95], v[162:165], v[176:179], v[80:95]
	v_exp_f32_e32 v112, v112
	v_exp_f32_e32 v113, v113
	v_exp_f32_e32 v114, v114
	v_exp_f32_e32 v115, v115
	v_mfma_f32_32x32x16_bf16 v[200:215], v[162:165], v[180:183], v[200:215]
	v_exp_f32_e32 v116, v116
	v_exp_f32_e32 v117, v117
	v_exp_f32_e32 v118, v118
	v_exp_f32_e32 v119, v119
	v_cvt_pk_bf16_f32 v162, v112, v113
	v_cvt_pk_bf16_f32 v163, v114, v115
	v_cvt_pk_bf16_f32 v164, v116, v117
	v_cvt_pk_bf16_f32 v165, v118, v119
	v_pk_add_f32 v[130:131], v[130:131], v[112:113]
	v_pk_add_f32 v[130:131], v[130:131], v[114:115]
	v_pk_add_f32 v[130:131], v[130:131], v[116:117]
	v_pk_add_f32 v[130:131], v[130:131], v[118:119]
	v_mfma_f32_32x32x16_bf16 v[80:95], v[162:165], v[184:187], v[80:95]
	v_exp_f32_e32 v120, v120
	v_exp_f32_e32 v121, v121
	v_exp_f32_e32 v122, v122
	v_exp_f32_e32 v123, v123
	v_mfma_f32_32x32x16_bf16 v[200:215], v[162:165], v[188:191], v[200:215]
	v_exp_f32_e32 v124, v124
	v_exp_f32_e32 v125, v125
	v_exp_f32_e32 v126, v126
	v_exp_f32_e32 v127, v127
	v_cvt_pk_bf16_f32 v162, v120, v121
	v_cvt_pk_bf16_f32 v163, v122, v123
	v_cvt_pk_bf16_f32 v164, v124, v125
	v_cvt_pk_bf16_f32 v165, v126, v127
	v_pk_add_f32 v[130:131], v[130:131], v[120:121]
	v_pk_add_f32 v[130:131], v[130:131], v[122:123]
	v_pk_add_f32 v[130:131], v[130:131], v[124:125]
	v_pk_add_f32 v[130:131], v[130:131], v[126:127]
	s_cmp_eq_u32 s33, 21
	s_cbranch_scc1 .Lat_w0g3
	s_waitcnt vmcnt(4)
	s_branch .Lat_wdg3

; #define AT_LOAD(K0, K1, V0, V1, T) do { const size_t e_ = (size_t)(128 * (T) + sr) * 64 + sc; \
;         K0 = *(const bf16x8*)(kcp + e_); V0 = *(const bf16x8*)(vcp + e_); K1 = *(const bf16x8*)(kcp + e_ + 64 * 64); V1 = *(const bf16x8*)(vcp + e_ + 64 * 64); } while (0)
; #define AT_STORE(K0, K1, V0, V1, BUF) do { *(LAS bf16x8*)(lds + AT_K + (BUF) * AT_KB + kst0) = K0; *(LAS bf16x8*)(lds + AT_K + (BUF) * AT_KB + kst1) = K1; \
;         *(LAS bf16x8*)(lds + AT_V + (BUF) * AT_VB + vst0) = V0; *(LAS bf16x8*)(lds + AT_V + (BUF) * AT_VB + vst1) = V1; } while (0)
; template <int VAR>
; __device__ __forceinline__ void attn_unit(const Args& a, int l, int b, int h, int qrow0  , bool ctxu, const bf16* Z, bf16* Y, LAS unsigned char* lds) {
;     ...
;     for (int t = 0; t < NT; t += 2) {
;         __syncthreads();
;         if (t + 2 < NT) AT_LOAD(ka0, ka1, va0, va1, t + 2);
;         attn_tile(Kb0, vb0, q0, q1, negm, m, o0, o1, lacc, t == 0, wsf, r32, hi);
;         AT_STORE(kb0, kb1, vb0_, vb1_, 1);
;         __syncthreads();
;         if (t + 3 < NT) AT_LOAD(kb0, kb1, vb0_, vb1_, t + 3);
;         attn_tile(Kb0 + AT_KB, vb0 + AT_VB, q0, q1, negm, m, o0, o1, lacc, false, wsf, r32, hi);
;         if (t + 2 < NT) AT_STORE(ka0, ka1, va0, va1, 0);
.Lat_wdg3:
	s_waitcnt lgkmcnt(0)
	s_barrier
	s_cmp_eq_u32 s33, 21
	s_cbranch_scc1 .Lat_ndg3
	s_add_u32 m0, s51, 0x4000
	s_nop 0
	global_load_lds_dwordx4 v158, s[36:37]
	s_add_u32 m0, s51, 0x6000
	s_nop 0
	global_load_lds_dwordx4 v159, s[36:37]
	s_add_u32 m0, s51, 0x10000
	s_nop 0
	global_load_lds_dwordx4 v160, s[48:49]
	s_add_u32 m0, s51, 0x12000
	s_nop 0
	global_load_lds_dwordx4 v161, s[48:49]
	s_add_u32 s36, s36, 0x4000
	s_addc_u32 s37, s37, 0
	s_add_u32 s48, s48, 0x4000
	s_addc_u32 s49, s49, 0
.Lat_ndg3:
	ds_read_b128 v[48:51], v144 offset:32768
	ds_read_b128 v[52:55], v145 offset:32768
	ds_read_b128 v[56:59], v144 offset:36864
	ds_read_b128 v[60:63], v145 offset:36864
	v_mfma_f32_32x32x16_bf16 v[80:95], v[162:165], v[192:195], v[80:95]
	v_mfma_f32_32x32x16_bf16 v[200:215], v[162:165], v[196:199], v[200:215]
	s_waitcnt lgkmcnt(0)
	v_mfma_f32_32x32x16_bf16 v[96:111], v[48:51], v[136:139], v[32:47]
	ds_read_b64_tr_b16 v[168:169], v146 offset:32768
	ds_read_b64_tr_b16 v[170:171], v146 offset:33792
	ds_read_b64_tr_b16 v[172:173], v146 offset:33280
	ds_read_b64_tr_b16 v[174:175], v146 offset:34304
	v_mfma_f32_32x32x16_bf16 v[96:111], v[52:55], v[140:143], v[96:111]
	ds_read_b64_tr_b16 v[176:177], v146 offset:34816
	ds_read_b64_tr_b16 v[178:179], v146 offset:35840
	ds_read_b64_tr_b16 v[180:181], v146 offset:35328
	ds_read_b64_tr_b16 v[182:183], v146 offset:36352
	v_mfma_f32_32x32x16_bf16 v[112:127], v[56:59], v[136:139], v[32:47]
	ds_read_b64_tr_b16 v[184:185], v146 offset:36864
	ds_read_b64_tr_b16 v[186:187], v146 offset:37888
	ds_read_b64_tr_b16 v[188:189], v146 offset:37376
	ds_read_b64_tr_b16 v[190:191], v146 offset:38400
	v_mfma_f32_32x32x16_bf16 v[112:127], v[60:63], v[140:143], v[112:127]
	ds_read_b64_tr_b16 v[192:193], v146 offset:38912
	ds_read_b64_tr_b16 v[194:195], v146 offset:39936
	ds_read_b64_tr_b16 v[196:197], v146 offset:39424
	ds_read_b64_tr_b16 v[198:199], v146 offset:40448
	v_max3_f32 v132, v96, v97, v98
	v_max3_f32 v133, v99, v100, v101
	v_max3_f32 v132, v132, v102, v103
	v_max3_f32 v133, v133, v104, v105
	v_max3_f32 v132, v132, v106, v107
	v_max3_f32 v133, v133, v108, v109
	v_max3_f32 v132, v132, v110, v111
	s_nop 1
	v_max3_f32 v133, v133, v112, v113
	v_max3_f32 v132, v132, v114, v115
	v_max3_f32 v133, v133, v116, v117
	v_max3_f32 v132, v132, v118, v119
	v_max3_f32 v133, v133, v120, v121
	v_max3_f32 v132, v132, v122, v123
	v_max3_f32 v133, v133, v124, v125
	v_max3_f32 v132, v132, v126, v127
	v_max_f32_e32 v132, v132, v133
	v_mov_b32_e32 v133, v132
	s_nop 1
	v_permlane32_swap_b32_e32 v132, v133
	v_max_f32_e32 v132, v132, v133
	v_cmp_lt_f32_e32 vcc, s4, v132
	s_cbranch_vccnz .Lat_rareg4a
.Lat_backg4a:
	v_exp_f32_e32 v96, v96
	v_exp_f32_e32 v97, v97
	v_exp_f32_e32 v98, v98
	v_exp_f32_e32 v99, v99
	v_exp_f32_e32 v100, v100
	v_exp_f32_e32 v101, v101
	v_exp_f32_e32 v102, v102
	v_exp_f32_e32 v103, v103
	v_cvt_pk_bf16_f32 v162, v96, v97
	v_cvt_pk_bf16_f32 v163, v98, v99
	v_cvt_pk_bf16_f32 v164, v100, v101
	v_cvt_pk_bf16_f32 v165, v102, v103
	v_pk_add_f32 v[128:129], v[128:129], v[96:97]
	v_pk_add_f32 v[128:129], v[128:129], v[98:99]
	v_pk_add_f32 v[128:129], v[128:129], v[100:101]
	v_pk_add_f32 v[128:129], v[128:129], v[102:103]
	s_waitcnt lgkmcnt(12)
	v_mfma_f32_32x32x16_bf16 v[0:15], v[162:165], v[168:171], v[0:15]
	v_exp_f32_e32 v104, v104
	v_exp_f32_e32 v105, v105
	v_exp_f32_e32 v106, v106
	v_exp_f32_e32 v107, v107
	v_mfma_f32_32x32x16_bf16 v[16:31], v[162:165], v[172:175], v[16:31]
	v_exp_f32_e32 v108, v108
	v_exp_f32_e32 v109, v109
	v_exp_f32_e32 v110, v110
	v_exp_f32_e32 v111, v111
	v_cvt_pk_bf16_f32 v162, v104, v105
	v_cvt_pk_bf16_f32 v163, v106, v107
	v_cvt_pk_bf16_f32 v164, v108, v109
	v_cvt_pk_bf16_f32 v165, v110, v111
	v_pk_add_f32 v[128:129], v[128:129], v[104:105]
	v_pk_add_f32 v[128:129], v[128:129], v[106:107]
	v_pk_add_f32 v[128:129], v[128:129], v[108:109]
	v_pk_add_f32 v[128:129], v[128:129], v[110:111]
	s_waitcnt lgkmcnt(8)
	v_mfma_f32_32x32x16_bf16 v[0:15], v[162:165], v[176:179], v[0:15]
	v_exp_f32_e32 v112, v112
	v_exp_f32_e32 v113, v113
	v_exp_f32_e32 v114, v114
	v_exp_f32_e32 v115, v115
	v_mfma_f32_32x32x16_bf16 v[16:31], v[162:165], v[180:183], v[16:31]
	v_mfma_f32_32x32x16_bf16 v[96:111], v[48:51], v[150:153], v[64:79]
	v_exp_f32_e32 v116, v116
	v_exp_f32_e32 v117, v117
	v_exp_f32_e32 v118, v118
	v_exp_f32_e32 v119, v119
	v_mfma_f32_32x32x16_bf16 v[96:111], v[52:55], v[154:157], v[96:111]
	v_cvt_pk_bf16_f32 v162, v112, v113
	v_cvt_pk_bf16_f32 v163, v114, v115
	v_cvt_pk_bf16_f32 v164, v116, v117
	v_cvt_pk_bf16_f32 v165, v118, v119
	v_pk_add_f32 v[128:129], v[128:129], v[112:113]
	v_pk_add_f32 v[128:129], v[128:129], v[114:115]
	v_pk_add_f32 v[128:129], v[128:129], v[116:117]
	v_pk_add_f32 v[128:129], v[128:129], v[118:119]
	s_waitcnt lgkmcnt(4)
	v_mfma_f32_32x32x16_bf16 v[0:15], v[162:165], v[184:187], v[0:15]
	v_exp_f32_e32 v120, v120
	v_exp_f32_e32 v121, v121
	v_exp_f32_e32 v122, v122
	v_exp_f32_e32 v123, v123
	v_mfma_f32_32x32x16_bf16 v[16:31], v[162:165], v[188:191], v[16:31]
	v_exp_f32_e32 v124, v124
	v_exp_f32_e32 v125, v125
	v_exp_f32_e32 v126, v126
	v_exp_f32_e32 v127, v127
	v_cvt_pk_bf16_f32 v162, v120, v121
	v_cvt_pk_bf16_f32 v163, v122, v123
	v_cvt_pk_bf16_f32 v164, v124, v125
	v_cvt_pk_bf16_f32 v165, v126, v127
	v_pk_add_f32 v[128:129], v[128:129], v[120:121]
	v_pk_add_f32 v[128:129], v[128:129], v[122:123]
	v_pk_add_f32 v[128:129], v[128:129], v[124:125]
	v_pk_add_f32 v[128:129], v[128:129], v[126:127]
	s_waitcnt lgkmcnt(0)
	v_mfma_f32_32x32x16_bf16 v[0:15], v[162:165], v[192:195], v[0:15]
	v_mfma_f32_32x32x16_bf16 v[16:31], v[162:165], v[196:199], v[16:31]
	v_mfma_f32_32x32x16_bf16 v[112:127], v[56:59], v[150:153], v[64:79]
	v_mfma_f32_32x32x16_bf16 v[112:127], v[60:63], v[154:157], v[112:127]
	ds_read_b128 v[48:51], v144 offset:40960
	ds_read_b128 v[52:55], v145 offset:40960
	ds_read_b128 v[56:59], v144 offset:45056
	ds_read_b128 v[60:63], v145 offset:45056
	v_max3_f32 v132, v96, v97, v98
	v_max3_f32 v133, v99, v100, v101
	v_max3_f32 v132, v132, v102, v103
	v_max3_f32 v133, v133, v104, v105
	v_max3_f32 v132, v132, v106, v107
	v_max3_f32 v133, v133, v108, v109
	v_max3_f32 v132, v132, v110, v111
	s_nop 1
	v_max3_f32 v133, v133, v112, v113
	v_max3_f32 v132, v132, v114, v115
	v_max3_f32 v133, v133, v116, v117
	v_max3_f32 v132, v132, v118, v119
	v_max3_f32 v133, v133, v120, v121
	v_max3_f32 v132, v132, v122, v123
	v_max3_f32 v133, v133, v124, v125
	v_max3_f32 v132, v132, v126, v127
	v_max_f32_e32 v132, v132, v133
	v_mov_b32_e32 v133, v132
	s_nop 1
	v_permlane32_swap_b32_e32 v132, v133
	v_max_f32_e32 v132, v132, v133
	v_cmp_lt_f32_e32 vcc, s4, v132
	s_cbranch_vccnz .Lat_rareg4b
.Lat_backg4b:
	v_exp_f32_e32 v96, v96
	v_exp_f32_e32 v97, v97
	v_exp_f32_e32 v98, v98
	v_exp_f32_e32 v99, v99
	v_exp_f32_e32 v100, v100
	v_exp_f32_e32 v101, v101
	v_exp_f32_e32 v102, v102
	v_exp_f32_e32 v103, v103
	v_cvt_pk_bf16_f32 v162, v96, v97
	v_cvt_pk_bf16_f32 v163, v98, v99
	v_cvt_pk_bf16_f32 v164, v100, v101
	v_cvt_pk_bf16_f32 v165, v102, v103
	v_pk_add_f32 v[130:131], v[130:131], v[96:97]
	v_pk_add_f32 v[130:131], v[130:131], v[98:99]
	v_pk_add_f32 v[130:131], v[130:131], v[100:101]
	v_pk_add_f32 v[130:131], v[130:131], v[102:103]
	v_mfma_f32_32x32x16_bf16 v[80:95], v[162:165], v[168:171], v[80:95]
	v_exp_f32_e32 v104, v104
	v_exp_f32_e32 v105, v105
	v_exp_f32_e32 v106, v106
	v_exp_f32_e32 v107, v107
	v_mfma_f32_32x32x16_bf16 v[200:215], v[162:165], v[172:175], v[200:215]
	v_exp_f32_e32 v108, v108
	v_exp_f32_e32 v109, v109
	v_exp_f32_e32 v110, v110
	v_exp_f32_e32 v111, v111
	v_cvt_pk_bf16_f32 v162, v104, v105
	v_cvt_pk_bf16_f32 v163, v106, v107
	v_cvt_pk_bf16_f32 v164, v108, v109
	v_cvt_pk_bf16_f32 v165, v110, v111
	v_pk_add_f32 v[130:131], v[130:131], v[104:105]
	v_pk_add_f32 v[130:131], v[130:131], v[106:107]
	v_pk_add_f32 v[130:131], v[130:131], v[108:109]
	v_pk_add_f32 v[130:131], v[130:131], v[110:111]
	v_mfma_f32_32x32x16_bf16 v[80:95], v[162:165], v[176:179], v[80:95]
	v_exp_f32_e32 v112, v112
	v_exp_f32_e32 v113, v113
	v_exp_f32_e32 v114, v114
	v_exp_f32_e32 v115, v115
	v_mfma_f32_32x32x16_bf16 v[200:215], v[162:165], v[180:183], v[200:215]
	v_exp_f32_e32 v116, v116
	v_exp_f32_e32 v117, v117
	v_exp_f32_e32 v118, v118
	v_exp_f32_e32 v119, v119
	v_cvt_pk_bf16_f32 v162, v112, v113
	v_cvt_pk_bf16_f32 v163, v114, v115
	v_cvt_pk_bf16_f32 v164, v116, v117
	v_cvt_pk_bf16_f32 v165, v118, v119
	v_pk_add_f32 v[130:131], v[130:131], v[112:113]
	v_pk_add_f32 v[130:131], v[130:131], v[114:115]
	v_pk_add_f32 v[130:131], v[130:131], v[116:117]
	v_pk_add_f32 v[130:131], v[130:131], v[118:119]
	v_mfma_f32_32x32x16_bf16 v[80:95], v[162:165], v[184:187], v[80:95]
	v_exp_f32_e32 v120, v120
	v_exp_f32_e32 v121, v121
	v_exp_f32_e32 v122, v122
	v_exp_f32_e32 v123, v123
	v_mfma_f32_32x32x16_bf16 v[200:215], v[162:165], v[188:191], v[200:215]
	v_exp_f32_e32 v124, v124
	v_exp_f32_e32 v125, v125
	v_exp_f32_e32 v126, v126
	v_exp_f32_e32 v127, v127
	v_cvt_pk_bf16_f32 v162, v120, v121
	v_cvt_pk_bf16_f32 v163, v122, v123
	v_cvt_pk_bf16_f32 v164, v124, v125
	v_cvt_pk_bf16_f32 v165, v126, v127
	v_pk_add_f32 v[130:131], v[130:131], v[120:121]
	v_pk_add_f32 v[130:131], v[130:131], v[122:123]
	v_pk_add_f32 v[130:131], v[130:131], v[124:125]
	v_pk_add_f32 v[130:131], v[130:131], v[126:127]
	v_mfma_f32_32x32x16_bf16 v[80:95], v[162:165], v[192:195], v[80:95]
	v_mfma_f32_32x32x16_bf16 v[200:215], v[162:165], v[196:199], v[200:215]
	s_waitcnt lgkmcnt(0)
	v_mfma_f32_32x32x16_bf16 v[96:111], v[48:51], v[136:139], v[32:47]
	ds_read_b64_tr_b16 v[168:169], v146 offset:40960
	ds_read_b64_tr_b16 v[170:171], v146 offset:41984
	ds_read_b64_tr_b16 v[172:173], v146 offset:41472
	ds_read_b64_tr_b16 v[174:175], v146 offset:42496
	v_mfma_f32_32x32x16_bf16 v[96:111], v[52:55], v[140:143], v[96:111]
	ds_read_b64_tr_b16 v[176:177], v146 offset:43008
	ds_read_b64_tr_b16 v[178:179], v146 offset:44032
	ds_read_b64_tr_b16 v[180:181], v146 offset:43520
	ds_read_b64_tr_b16 v[182:183], v146 offset:44544
	v_mfma_f32_32x32x16_bf16 v[112:127], v[56:59], v[136:139], v[32:47]
	ds_read_b64_tr_b16 v[184:185], v146 offset:45056
	ds_read_b64_tr_b16 v[186:187], v146 offset:46080
	ds_read_b64_tr_b16 v[188:189], v146 offset:45568
	ds_read_b64_tr_b16 v[190:191], v146 offset:46592
	v_mfma_f32_32x32x16_bf16 v[112:127], v[60:63], v[140:143], v[112:127]
	ds_read_b64_tr_b16 v[192:193], v146 offset:47104
	ds_read_b64_tr_b16 v[194:195], v146 offset:48128
	ds_read_b64_tr_b16 v[196:197], v146 offset:47616
	ds_read_b64_tr_b16 v[198:199], v146 offset:48640
	v_max3_f32 v132, v96, v97, v98
	v_max3_f32 v133, v99, v100, v101
	v_max3_f32 v132, v132, v102, v103
	v_max3_f32 v133, v133, v104, v105
	v_max3_f32 v132, v132, v106, v107
	v_max3_f32 v133, v133, v108, v109
	v_max3_f32 v132, v132, v110, v111
	s_nop 1
	v_max3_f32 v133, v133, v112, v113
	v_max3_f32 v132, v132, v114, v115
	v_max3_f32 v133, v133, v116, v117
	v_max3_f32 v132, v132, v118, v119
	v_max3_f32 v133, v133, v120, v121
	v_max3_f32 v132, v132, v122, v123
	v_max3_f32 v133, v133, v124, v125
	v_max3_f32 v132, v132, v126, v127
	v_max_f32_e32 v132, v132, v133
	v_mov_b32_e32 v133, v132
	s_nop 1
	v_permlane32_swap_b32_e32 v132, v133
	v_max_f32_e32 v132, v132, v133
	v_cmp_lt_f32_e32 vcc, s4, v132
	s_cbranch_vccnz .Lat_rareg5a

; #define LAS __attribute__((address_space(3)))
; __device__ __forceinline__ int crow(int r, int hi) { return (r & 3) + 8 * (r >> 2) + 4 * hi; }
; #define AT_LOAD(K0, K1, V0, V1, T) do { const size_t e_ = (size_t)(128 * (T) + sr) * 64 + sc; \
;         K0 = *(const bf16x8*)(kcp + e_); V0 = *(const bf16x8*)(vcp + e_); K1 = *(const bf16x8*)(kcp + e_ + 64 * 64); V1 = *(const bf16x8*)(vcp + e_ + 64 * 64); } while (0)
; #define AT_STORE(K0, K1, V0, V1, BUF) do { *(LAS bf16x8*)(lds + AT_K + (BUF) * AT_KB + kst0) = K0; *(LAS bf16x8*)(lds + AT_K + (BUF) * AT_KB + kst1) = K1; \
;         *(LAS bf16x8*)(lds + AT_V + (BUF) * AT_VB + vst0) = V0; *(LAS bf16x8*)(lds + AT_V + (BUF) * AT_VB + vst1) = V1; } while (0)
; template <int VAR>
; __device__ __forceinline__ void attn_unit(const Args& a, int l, int b, int h, int qrow0  , bool ctxu, const bf16* Z, bf16* Y, LAS unsigned char* lds) {
;     ...
;     for (int t = 0; t < NT; t += 2) {
;         __syncthreads();
;         if (t + 2 < NT) AT_LOAD(ka0, ka1, va0, va1, t + 2);
;         attn_tile(Kb0, vb0, q0, q1, negm, m, o0, o1, lacc, t == 0, wsf, r32, hi);
;         AT_STORE(kb0, kb1, vb0_, vb1_, 1);
;         __syncthreads();
;         if (t + 3 < NT) AT_LOAD(kb0, kb1, vb0_, vb1_, t + 3);
;         attn_tile(Kb0 + AT_KB, vb0 + AT_VB, q0, q1, negm, m, o0, o1, lacc, false, wsf, r32, hi);
;         if (t + 2 < NT) AT_STORE(ka0, ka1, va0, va1, 0);
;     }
;     ...
;     float lam, omli;
;     { float s1 = 0.f, s2 = 0.f;
;       for (int i = 0; i < 32; ++i) { s1 += a.lam_q1[l * 32 + i] * a.lam_k1[l * 32 + i]; s2 += a.lam_q2[l * 32 + i] * a.lam_k2[l * 32 + i]; }
;       const float li = 0.8f - 0.6f * expf(-0.3f * (float)l); lam = expf(s1) - expf(s2) + li; omli = 1.f - li; }
;     LAS float* stg = (LAS float*)(lds + AT_ST) + wq * 2048;
;     if (comp == 1) {
; #pragma unroll
;         for (int r = 0; r < 16; ++r) { const int qr = crow(r, hi); const float il = lam * __builtin_amdgcn_rcpf(lacc[r]); stg[qr * 64 + r32] = o0[r] * il; stg[qr * 64 + 32 + r32] = o1[r] * il; }
.Lat_wdg5:
	s_waitcnt lgkmcnt(0)
	s_barrier
	s_cmp_eq_u32 s33, 21
	s_cbranch_scc1 .Lat_ndg5
	s_add_u32 m0, s51, 0x8000
	s_nop 0
	global_load_lds_dwordx4 v158, s[36:37]
	s_add_u32 m0, s51, 0xa000
	s_nop 0
	global_load_lds_dwordx4 v159, s[36:37]
	s_add_u32 m0, s51, 0x14000
	s_nop 0
	global_load_lds_dwordx4 v160, s[48:49]
	s_add_u32 m0, s51, 0x16000
	s_nop 0
	global_load_lds_dwordx4 v161, s[48:49]
	s_add_u32 s36, s36, 0x4000
	s_addc_u32 s37, s37, 0
	s_add_u32 s48, s48, 0x4000
	s_addc_u32 s49, s49, 0
.Lat_ndg5:
	ds_read_b128 v[48:51], v144 offset:0
	ds_read_b128 v[52:55], v145 offset:0
	ds_read_b128 v[56:59], v144 offset:4096
	ds_read_b128 v[60:63], v145 offset:4096
	v_mfma_f32_32x32x16_bf16 v[80:95], v[162:165], v[192:195], v[80:95]
	v_mfma_f32_32x32x16_bf16 v[200:215], v[162:165], v[196:199], v[200:215]
	s_add_u32 s33, s33, 1
	s_cmp_lt_u32 s33, 22
	s_cbranch_scc1 .Lat_loop
	v_add_f32_e32 v132, v128, v129
	v_mov_b32_e32 v133, v132
	s_nop 1
	v_permlane32_swap_b32_e32 v132, v133
	v_add_f32_e32 v135, v132, v133
	v_add_f32_e32 v132, v130, v131
	v_mov_b32_e32 v133, v132
	s_nop 1
	v_permlane32_swap_b32_e32 v132, v133
	v_add_f32_e32 v130, v132, v133
	s_nop 7
	s_waitcnt lgkmcnt(0)
	ds_write_b32 v148, v135
	s_waitcnt lgkmcnt(0)
	ds_read_b128 v[32:35], v147 offset:0
	ds_read_b128 v[36:39], v147 offset:32
	ds_read_b128 v[40:43], v147 offset:64
	ds_read_b128 v[44:47], v147 offset:96
	s_waitcnt lgkmcnt(0)
	s_mov_b32 s93, 0
	s_waitcnt vmcnt(0)
	s_setprio 0
	s_branch .LBB0_459

; __global__ void __launch_bounds__(512, 2) fwd_megakernel(Args a) {
;     ...
;                 for (int i = 0;; ++i) { const int j = xm ? cu + i * per : blk + i * G; if (j >= (xm ? 128 : 1024)) break;
;                     const int bh = xm ? xcd * 2 + (j >> 6) : (j >> 6), qb = j & 63; if (rep_ == 0) attn_unit<0>(a, l, bh >> 2, bh & 3, (bh >> 2) * SEQ + qb * 128, false, Zb, Yb, lds); else attn_unit<PROBE_VAR>(a, l, bh >> 2, bh & 3, (bh >> 2) * SEQ + qb * 128, false, Zb, (bf16*)(ws + 384 * MiB), lds); }
.Lat_afterA:
	s_cmp_eq_u32 s93, 0
	s_cbranch_scc1 .Lat_passB
	s_add_i32 s59, s59, 1
	s_branch .LBB0_428
.Lat_passB:
	s_mov_b32 s93, 1
	s_barrier
	v_mov_b32_e32 v0, v80
	v_mov_b32_e32 v16, v200
	v_mov_b32_e32 v1, v81
	v_mov_b32_e32 v17, v201
	v_mov_b32_e32 v2, v82
	v_mov_b32_e32 v18, v202
	v_mov_b32_e32 v3, v83
	v_mov_b32_e32 v19, v203
	v_mov_b32_e32 v4, v84
	v_mov_b32_e32 v20, v204
	v_mov_b32_e32 v5, v85
	v_mov_b32_e32 v21, v205
	v_mov_b32_e32 v6, v86
	v_mov_b32_e32 v22, v206
	v_mov_b32_e32 v7, v87
	v_mov_b32_e32 v23, v207
	v_mov_b32_e32 v8, v88
	v_mov_b32_e32 v24, v208
	v_mov_b32_e32 v9, v89
	v_mov_b32_e32 v25, v209
	v_mov_b32_e32 v10, v90
	v_mov_b32_e32 v26, v210
	v_mov_b32_e32 v11, v91
	v_mov_b32_e32 v27, v211
	v_mov_b32_e32 v12, v92
	v_mov_b32_e32 v28, v212
	v_mov_b32_e32 v13, v93
	v_mov_b32_e32 v29, v213
	v_mov_b32_e32 v14, v94
	v_mov_b32_e32 v30, v214
	v_mov_b32_e32 v15, v95
	v_mov_b32_e32 v31, v215
	s_waitcnt lgkmcnt(0)
	ds_write_b32 v148, v130
	s_waitcnt lgkmcnt(0)
	ds_read_b128 v[32:35], v147 offset:0
	ds_read_b128 v[36:39], v147 offset:32
	ds_read_b128 v[40:43], v147 offset:64
	ds_read_b128 v[44:47], v147 offset:96
	s_waitcnt lgkmcnt(0)
	v_mbcnt_lo_u32_b32 v227, -1, 0
	v_mbcnt_hi_u32_b32 v227, -1, v227
	s_or_b32 s60, s60, 0x1000
	s_bfe_u32 s9, s29, 0x20006
	s_ashr_i32 s8, s29, 8
	s_branch .LBB0_459
.Lat_rareg0a:
	s_cmp_lg_u32 s94, 0
	s_cbranch_scc1 .Lat_firsta
	v_max_f32_e32 v132, 0, v132
	v_exp_f32_e64 v133, -v132
	v_add_f32_e32 v234, v234, v132
	s_nop 0
	ds_write_b32 v148, v133
	v_mul_f32_e32 v128, v128, v133
	v_mul_f32_e32 v129, v129, v133
	v_sub_f32_e32 v96, v96, v132
	v_sub_f32_e32 v97, v97, v132
	v_sub_f32_e32 v98, v98, v132
	v_sub_f32_e32 v99, v99, v132
	v_sub_f32_e32 v100, v100, v132
	v_sub_f32_e32 v101, v101, v132
	v_sub_f32_e32 v102, v102, v132
	v_sub_f32_e32 v103, v103, v132
	v_sub_f32_e32 v104, v104, v132
	v_sub_f32_e32 v105, v105, v132
	v_sub_f32_e32 v106, v106, v132
	v_sub_f32_e32 v107, v107, v132
	v_sub_f32_e32 v108, v108, v132
	v_sub_f32_e32 v109, v109, v132
	v_sub_f32_e32 v110, v110, v132
	v_sub_f32_e32 v111, v111, v132
	v_sub_f32_e32 v112, v112, v132
	v_sub_f32_e32 v113, v113, v132
	v_sub_f32_e32 v114, v114, v132
	v_sub_f32_e32 v115, v115, v132
	v_sub_f32_e32 v116, v116, v132
	v_sub_f32_e32 v117, v117, v132
	v_sub_f32_e32 v118, v118, v132
	v_sub_f32_e32 v119, v119, v132
	v_sub_f32_e32 v120, v120, v132
	v_sub_f32_e32 v121, v121, v132
	v_sub_f32_e32 v122, v122, v132
	v_sub_f32_e32 v123, v123, v132
	v_sub_f32_e32 v124, v124, v132
	v_sub_f32_e32 v125, v125, v132
	v_sub_f32_e32 v126, v126, v132
	v_sub_f32_e32 v127, v127, v132
	v_xor_b32_e32 v32, 0x80000000, v234
	v_mov_b32_e32 v33, v32
	v_mov_b32_e32 v34, v32
	v_mov_b32_e32 v35, v32
	v_mov_b32_e32 v36, v32
	v_mov_b32_e32 v37, v32
	v_mov_b32_e32 v38, v32
	v_mov_b32_e32 v39, v32
	v_mov_b32_e32 v40, v32
	v_mov_b32_e32 v41, v32
	v_mov_b32_e32 v42, v32
	v_mov_b32_e32 v43, v32
	v_mov_b32_e32 v44, v32
	v_mov_b32_e32 v45, v32
	v_mov_b32_e32 v46, v32
	v_mov_b32_e32 v47, v32
	s_waitcnt lgkmcnt(0)
	ds_read_b128 v[162:165], v147 offset:0
	s_waitcnt lgkmcnt(0)
	v_mul_f32_e32 v0, v0, v162
	v_mul_f32_e32 v16, v16, v162
	v_mul_f32_e32 v1, v1, v163
	v_mul_f32_e32 v17, v17, v163
	v_mul_f32_e32 v2, v2, v164
	v_mul_f32_e32 v18, v18, v164
	v_mul_f32_e32 v3, v3, v165
	v_mul_f32_e32 v19, v19, v165
	ds_read_b128 v[162:165], v147 offset:32
	s_waitcnt lgkmcnt(0)
	v_mul_f32_e32 v4, v4, v162
	v_mul_f32_e32 v20, v20, v162
	v_mul_f32_e32 v5, v5, v163
	v_mul_f32_e32 v21, v21, v163
	v_mul_f32_e32 v6, v6, v164
	v_mul_f32_e32 v22, v22, v164
	v_mul_f32_e32 v7, v7, v165
	v_mul_f32_e32 v23, v23, v165
	ds_read_b128 v[162:165], v147 offset:64
	s_waitcnt lgkmcnt(0)
	v_mul_f32_e32 v8, v8, v162
	v_mul_f32_e32 v24, v24, v162
	v_mul_f32_e32 v9, v9, v163
	v_mul_f32_e32 v25, v25, v163
	v_mul_f32_e32 v10, v10, v164
	v_mul_f32_e32 v26, v26, v164
	v_mul_f32_e32 v11, v11, v165
	v_mul_f32_e32 v27, v27, v165
	ds_read_b128 v[162:165], v147 offset:96
	s_waitcnt lgkmcnt(0)
	v_mul_f32_e32 v12, v12, v162
	v_mul_f32_e32 v28, v28, v162
	v_mul_f32_e32 v13, v13, v163
	v_mul_f32_e32 v29, v29, v163
	v_mul_f32_e32 v14, v14, v164
	v_mul_f32_e32 v30, v30, v164
	v_mul_f32_e32 v15, v15, v165
	v_mul_f32_e32 v31, v31, v165
	s_branch .Lat_backg0a
.Lat_firsta:
	v_mov_b32_e32 v234, v132
	v_sub_f32_e32 v96, v96, v132
	v_sub_f32_e32 v97, v97, v132
	v_sub_f32_e32 v98, v98, v132
	v_sub_f32_e32 v99, v99, v132
	v_sub_f32_e32 v100, v100, v132
	v_sub_f32_e32 v101, v101, v132
	v_sub_f32_e32 v102, v102, v132
	v_sub_f32_e32 v103, v103, v132
	v_sub_f32_e32 v104, v104, v132
	v_sub_f32_e32 v105, v105, v132
	v_sub_f32_e32 v106, v106, v132
	v_sub_f32_e32 v107, v107, v132
	v_sub_f32_e32 v108, v108, v132
	v_sub_f32_e32 v109, v109, v132
	v_sub_f32_e32 v110, v110, v132
	v_sub_f32_e32 v111, v111, v132
	v_sub_f32_e32 v112, v112, v132
	v_sub_f32_e32 v113, v113, v132
	v_sub_f32_e32 v114, v114, v132
	v_sub_f32_e32 v115, v115, v132
	v_sub_f32_e32 v116, v116, v132
	v_sub_f32_e32 v117, v117, v132
	v_sub_f32_e32 v118, v118, v132
	v_sub_f32_e32 v119, v119, v132
	v_sub_f32_e32 v120, v120, v132
	v_sub_f32_e32 v121, v121, v132
	v_sub_f32_e32 v122, v122, v132
	v_sub_f32_e32 v123, v123, v132
	v_sub_f32_e32 v124, v124, v132
	v_sub_f32_e32 v125, v125, v132
	v_sub_f32_e32 v126, v126, v132
	v_sub_f32_e32 v127, v127, v132
	v_xor_b32_e32 v32, 0x80000000, v234
	v_mov_b32_e32 v33, v32
	v_mov_b32_e32 v34, v32
	v_mov_b32_e32 v35, v32
	v_mov_b32_e32 v36, v32
	v_mov_b32_e32 v37, v32
	v_mov_b32_e32 v38, v32
	v_mov_b32_e32 v39, v32
	v_mov_b32_e32 v40, v32
	v_mov_b32_e32 v41, v32
	v_mov_b32_e32 v42, v32
	v_mov_b32_e32 v43, v32
	v_mov_b32_e32 v44, v32
	v_mov_b32_e32 v45, v32
	v_mov_b32_e32 v46, v32
	v_mov_b32_e32 v47, v32
	s_mov_b32 s94, 0
	s_branch .Lat_backg0a
.Lat_rareg0b:
	s_cmp_lg_u32 s95, 0
	s_cbranch_scc1 .Lat_firstb
	v_max_f32_e32 v132, 0, v132
	v_exp_f32_e64 v133, -v132
	v_add_f32_e32 v149, v149, v132
	s_nop 0
	ds_write_b32 v148, v133
	v_mul_f32_e32 v130, v130, v133
	v_mul_f32_e32 v131, v131, v133
	v_sub_f32_e32 v96, v96, v132
	v_sub_f32_e32 v97, v97, v132
	v_sub_f32_e32 v98, v98, v132
	v_sub_f32_e32 v99, v99, v132
	v_sub_f32_e32 v100, v100, v132
	v_sub_f32_e32 v101, v101, v132
	v_sub_f32_e32 v102, v102, v132
	v_sub_f32_e32 v103, v103, v132
	v_sub_f32_e32 v104, v104, v132
	v_sub_f32_e32 v105, v105, v132
	v_sub_f32_e32 v106, v106, v132
	v_sub_f32_e32 v107, v107, v132
	v_sub_f32_e32 v108, v108, v132
	v_sub_f32_e32 v109, v109, v132
	v_sub_f32_e32 v110, v110, v132
	v_sub_f32_e32 v111, v111, v132
	v_sub_f32_e32 v112, v112, v132
	v_sub_f32_e32 v113, v113, v132
	v_sub_f32_e32 v114, v114, v132
	v_sub_f32_e32 v115, v115, v132
	v_sub_f32_e32 v116, v116, v132
	v_sub_f32_e32 v117, v117, v132
	v_sub_f32_e32 v118, v118, v132
	v_sub_f32_e32 v119, v119, v132
	v_sub_f32_e32 v120, v120, v132
	v_sub_f32_e32 v121, v121, v132
	v_sub_f32_e32 v122, v122, v132
	v_sub_f32_e32 v123, v123, v132
	v_sub_f32_e32 v124, v124, v132
	v_sub_f32_e32 v125, v125, v132
	v_sub_f32_e32 v126, v126, v132
	v_sub_f32_e32 v127, v127, v132
	v_xor_b32_e32 v64, 0x80000000, v149
	v_mov_b32_e32 v65, v64
	v_mov_b32_e32 v66, v64
	v_mov_b32_e32 v67, v64
	v_mov_b32_e32 v68, v64
	v_mov_b32_e32 v69, v64
	v_mov_b32_e32 v70, v64
	v_mov_b32_e32 v71, v64
	v_mov_b32_e32 v72, v64
	v_mov_b32_e32 v73, v64
	v_mov_b32_e32 v74, v64
	v_mov_b32_e32 v75, v64
	v_mov_b32_e32 v76, v64
	v_mov_b32_e32 v77, v64
	v_mov_b32_e32 v78, v64
	v_mov_b32_e32 v79, v64
	s_waitcnt lgkmcnt(0)
	ds_read_b128 v[162:165], v147 offset:0
	s_waitcnt lgkmcnt(0)
	v_mul_f32_e32 v80, v80, v162
	v_mul_f32_e32 v200, v200, v162
	v_mul_f32_e32 v81, v81, v163
	v_mul_f32_e32 v201, v201, v163
	v_mul_f32_e32 v82, v82, v164
	v_mul_f32_e32 v202, v202, v164
	v_mul_f32_e32 v83, v83, v165
	v_mul_f32_e32 v203, v203, v165
	ds_read_b128 v[162:165], v147 offset:32
	s_waitcnt lgkmcnt(0)
	v_mul_f32_e32 v84, v84, v162
	v_mul_f32_e32 v204, v204, v162
	v_mul_f32_e32 v85, v85, v163
	v_mul_f32_e32 v205, v205, v163
	v_mul_f32_e32 v86, v86, v164
	v_mul_f32_e32 v206, v206, v164
	v_mul_f32_e32 v87, v87, v165
	v_mul_f32_e32 v207, v207, v165
	ds_read_b128 v[162:165], v147 offset:64
	s_waitcnt lgkmcnt(0)
	v_mul_f32_e32 v88, v88, v162
	v_mul_f32_e32 v208, v208, v162
	v_mul_f32_e32 v89, v89, v163
	v_mul_f32_e32 v209, v209, v163
	v_mul_f32_e32 v90, v90, v164
	v_mul_f32_e32 v210, v210, v164
	v_mul_f32_e32 v91, v91, v165
	v_mul_f32_e32 v211, v211, v165
	ds_read_b128 v[162:165], v147 offset:96
	s_waitcnt lgkmcnt(0)
	v_mul_f32_e32 v92, v92, v162
	v_mul_f32_e32 v212, v212, v162
	v_mul_f32_e32 v93, v93, v163
	v_mul_f32_e32 v213, v213, v163
	v_mul_f32_e32 v94, v94, v164
	v_mul_f32_e32 v214, v214, v164
	v_mul_f32_e32 v95, v95, v165
	v_mul_f32_e32 v215, v215, v165
	s_branch .Lat_backg0b
.Lat_firstb:
	v_mov_b32_e32 v149, v132
	v_sub_f32_e32 v96, v96, v132
	v_sub_f32_e32 v97, v97, v132
	v_sub_f32_e32 v98, v98, v132
	v_sub_f32_e32 v99, v99, v132
	v_sub_f32_e32 v100, v100, v132
	v_sub_f32_e32 v101, v101, v132
	v_sub_f32_e32 v102, v102, v132
	v_sub_f32_e32 v103, v103, v132
	v_sub_f32_e32 v104, v104, v132
	v_sub_f32_e32 v105, v105, v132
	v_sub_f32_e32 v106, v106, v132
	v_sub_f32_e32 v107, v107, v132
	v_sub_f32_e32 v108, v108, v132
	v_sub_f32_e32 v109, v109, v132
	v_sub_f32_e32 v110, v110, v132
	v_sub_f32_e32 v111, v111, v132
	v_sub_f32_e32 v112, v112, v132
	v_sub_f32_e32 v113, v113, v132
	v_sub_f32_e32 v114, v114, v132
	v_sub_f32_e32 v115, v115, v132
	v_sub_f32_e32 v116, v116, v132
	v_sub_f32_e32 v117, v117, v132
	v_sub_f32_e32 v118, v118, v132
	v_sub_f32_e32 v119, v119, v132
	v_sub_f32_e32 v120, v120, v132
	v_sub_f32_e32 v121, v121, v132
	v_sub_f32_e32 v122, v122, v132
	v_sub_f32_e32 v123, v123, v132
	v_sub_f32_e32 v124, v124, v132
	v_sub_f32_e32 v125, v125, v132
	v_sub_f32_e32 v126, v126, v132
	v_sub_f32_e32 v127, v127, v132
	v_xor_b32_e32 v64, 0x80000000, v149
	v_mov_b32_e32 v65, v64
	v_mov_b32_e32 v66, v64
	v_mov_b32_e32 v67, v64
	v_mov_b32_e32 v68, v64
	v_mov_b32_e32 v69, v64
	v_mov_b32_e32 v70, v64
	v_mov_b32_e32 v71, v64
	v_mov_b32_e32 v72, v64
	v_mov_b32_e32 v73, v64
	v_mov_b32_e32 v74, v64
	v_mov_b32_e32 v75, v64
	v_mov_b32_e32 v76, v64
	v_mov_b32_e32 v77, v64
	v_mov_b32_e32 v78, v64
	v_mov_b32_e32 v79, v64
	s_mov_b32 s95, 0
	s_branch .Lat_backg0b
.Lat_rareg1a:
	v_max_f32_e32 v132, 0, v132
	v_exp_f32_e64 v133, -v132
	v_add_f32_e32 v234, v234, v132
	s_nop 0
	ds_write_b32 v148, v133
	v_mul_f32_e32 v128, v128, v133
	v_mul_f32_e32 v129, v129, v133
	v_sub_f32_e32 v96, v96, v132
	v_sub_f32_e32 v97, v97, v132
	v_sub_f32_e32 v98, v98, v132
	v_sub_f32_e32 v99, v99, v132
	v_sub_f32_e32 v100, v100, v132
	v_sub_f32_e32 v101, v101, v132
	v_sub_f32_e32 v102, v102, v132
	v_sub_f32_e32 v103, v103, v132
	v_sub_f32_e32 v104, v104, v132
	v_sub_f32_e32 v105, v105, v132
	v_sub_f32_e32 v106, v106, v132
	v_sub_f32_e32 v107, v107, v132
	v_sub_f32_e32 v108, v108, v132
	v_sub_f32_e32 v109, v109, v132
	v_sub_f32_e32 v110, v110, v132
	v_sub_f32_e32 v111, v111, v132
	v_sub_f32_e32 v112, v112, v132
	v_sub_f32_e32 v113, v113, v132
	v_sub_f32_e32 v114, v114, v132
	v_sub_f32_e32 v115, v115, v132
	v_sub_f32_e32 v116, v116, v132
	v_sub_f32_e32 v117, v117, v132
	v_sub_f32_e32 v118, v118, v132
	v_sub_f32_e32 v119, v119, v132
	v_sub_f32_e32 v120, v120, v132
	v_sub_f32_e32 v121, v121, v132
	v_sub_f32_e32 v122, v122, v132
	v_sub_f32_e32 v123, v123, v132
	v_sub_f32_e32 v124, v124, v132
	v_sub_f32_e32 v125, v125, v132
	v_sub_f32_e32 v126, v126, v132
	v_sub_f32_e32 v127, v127, v132
	v_xor_b32_e32 v32, 0x80000000, v234
	v_mov_b32_e32 v33, v32
	v_mov_b32_e32 v34, v32
	v_mov_b32_e32 v35, v32
	v_mov_b32_e32 v36, v32
	v_mov_b32_e32 v37, v32
	v_mov_b32_e32 v38, v32
	v_mov_b32_e32 v39, v32
	v_mov_b32_e32 v40, v32
	v_mov_b32_e32 v41, v32
	v_mov_b32_e32 v42, v32
	v_mov_b32_e32 v43, v32
	v_mov_b32_e32 v44, v32
	v_mov_b32_e32 v45, v32
	v_mov_b32_e32 v46, v32
	v_mov_b32_e32 v47, v32
	s_waitcnt lgkmcnt(0)
	ds_read_b128 v[162:165], v147 offset:0
	s_waitcnt lgkmcnt(0)
	v_mul_f32_e32 v0, v0, v162
	v_mul_f32_e32 v16, v16, v162
	v_mul_f32_e32 v1, v1, v163
	v_mul_f32_e32 v17, v17, v163
	v_mul_f32_e32 v2, v2, v164
	v_mul_f32_e32 v18, v18, v164
	v_mul_f32_e32 v3, v3, v165
	v_mul_f32_e32 v19, v19, v165
	ds_read_b128 v[162:165], v147 offset:32
	s_waitcnt lgkmcnt(0)
	v_mul_f32_e32 v4, v4, v162
	v_mul_f32_e32 v20, v20, v162
	v_mul_f32_e32 v5, v5, v163
	v_mul_f32_e32 v21, v21, v163
	v_mul_f32_e32 v6, v6, v164
	v_mul_f32_e32 v22, v22, v164
	v_mul_f32_e32 v7, v7, v165
	v_mul_f32_e32 v23, v23, v165
	ds_read_b128 v[162:165], v147 offset:64
	s_waitcnt lgkmcnt(0)
	v_mul_f32_e32 v8, v8, v162
	v_mul_f32_e32 v24, v24, v162
	v_mul_f32_e32 v9, v9, v163
	v_mul_f32_e32 v25, v25, v163
	v_mul_f32_e32 v10, v10, v164
	v_mul_f32_e32 v26, v26, v164
	v_mul_f32_e32 v11, v11, v165
	v_mul_f32_e32 v27, v27, v165
	ds_read_b128 v[162:165], v147 offset:96
	s_waitcnt lgkmcnt(0)
	v_mul_f32_e32 v12, v12, v162
	v_mul_f32_e32 v28, v28, v162
	v_mul_f32_e32 v13, v13, v163
	v_mul_f32_e32 v29, v29, v163
	v_mul_f32_e32 v14, v14, v164
	v_mul_f32_e32 v30, v30, v164
	v_mul_f32_e32 v15, v15, v165
	v_mul_f32_e32 v31, v31, v165
	s_branch .Lat_backg1a
.Lat_rareg1b:
	v_max_f32_e32 v132, 0, v132
	v_exp_f32_e64 v133, -v132
	v_add_f32_e32 v149, v149, v132
	s_nop 0
	ds_write_b32 v148, v133
	v_mul_f32_e32 v130, v130, v133
	v_mul_f32_e32 v131, v131, v133
	v_sub_f32_e32 v96, v96, v132
	v_sub_f32_e32 v97, v97, v132
	v_sub_f32_e32 v98, v98, v132
	v_sub_f32_e32 v99, v99, v132
	v_sub_f32_e32 v100, v100, v132
	v_sub_f32_e32 v101, v101, v132
	v_sub_f32_e32 v102, v102, v132
	v_sub_f32_e32 v103, v103, v132
	v_sub_f32_e32 v104, v104, v132
	v_sub_f32_e32 v105, v105, v132
	v_sub_f32_e32 v106, v106, v132
	v_sub_f32_e32 v107, v107, v132
	v_sub_f32_e32 v108, v108, v132
	v_sub_f32_e32 v109, v109, v132
	v_sub_f32_e32 v110, v110, v132
	v_sub_f32_e32 v111, v111, v132
	v_sub_f32_e32 v112, v112, v132
	v_sub_f32_e32 v113, v113, v132
	v_sub_f32_e32 v114, v114, v132
	v_sub_f32_e32 v115, v115, v132
	v_sub_f32_e32 v116, v116, v132
	v_sub_f32_e32 v117, v117, v132
	v_sub_f32_e32 v118, v118, v132
	v_sub_f32_e32 v119, v119, v132
	v_sub_f32_e32 v120, v120, v132
	v_sub_f32_e32 v121, v121, v132
	v_sub_f32_e32 v122, v122, v132
	v_sub_f32_e32 v123, v123, v132
	v_sub_f32_e32 v124, v124, v132
	v_sub_f32_e32 v125, v125, v132
	v_sub_f32_e32 v126, v126, v132
	v_sub_f32_e32 v127, v127, v132
	v_xor_b32_e32 v64, 0x80000000, v149
	v_mov_b32_e32 v65, v64
	v_mov_b32_e32 v66, v64
	v_mov_b32_e32 v67, v64
	v_mov_b32_e32 v68, v64
	v_mov_b32_e32 v69, v64
	v_mov_b32_e32 v70, v64
	v_mov_b32_e32 v71, v64
	v_mov_b32_e32 v72, v64
	v_mov_b32_e32 v73, v64
	v_mov_b32_e32 v74, v64
	v_mov_b32_e32 v75, v64
	v_mov_b32_e32 v76, v64
	v_mov_b32_e32 v77, v64
	v_mov_b32_e32 v78, v64
	v_mov_b32_e32 v79, v64
	s_waitcnt lgkmcnt(0)
	ds_read_b128 v[162:165], v147 offset:0
	s_waitcnt lgkmcnt(0)
	v_mul_f32_e32 v80, v80, v162
	v_mul_f32_e32 v200, v200, v162
	v_mul_f32_e32 v81, v81, v163
	v_mul_f32_e32 v201, v201, v163
	v_mul_f32_e32 v82, v82, v164
	v_mul_f32_e32 v202, v202, v164
	v_mul_f32_e32 v83, v83, v165
	v_mul_f32_e32 v203, v203, v165
	ds_read_b128 v[162:165], v147 offset:32
	s_waitcnt lgkmcnt(0)
	v_mul_f32_e32 v84, v84, v162
	v_mul_f32_e32 v204, v204, v162
	v_mul_f32_e32 v85, v85, v163
	v_mul_f32_e32 v205, v205, v163
	v_mul_f32_e32 v86, v86, v164
	v_mul_f32_e32 v206, v206, v164
	v_mul_f32_e32 v87, v87, v165
	v_mul_f32_e32 v207, v207, v165
	ds_read_b128 v[162:165], v147 offset:64
	s_waitcnt lgkmcnt(0)
	v_mul_f32_e32 v88, v88, v162
	v_mul_f32_e32 v208, v208, v162
	v_mul_f32_e32 v89, v89, v163
	v_mul_f32_e32 v209, v209, v163
	v_mul_f32_e32 v90, v90, v164
	v_mul_f32_e32 v210, v210, v164
	v_mul_f32_e32 v91, v91, v165
	v_mul_f32_e32 v211, v211, v165
	ds_read_b128 v[162:165], v147 offset:96
	s_waitcnt lgkmcnt(0)
	v_mul_f32_e32 v92, v92, v162
	v_mul_f32_e32 v212, v212, v162
	v_mul_f32_e32 v93, v93, v163
	v_mul_f32_e32 v213, v213, v163
	v_mul_f32_e32 v94, v94, v164
	v_mul_f32_e32 v214, v214, v164
	v_mul_f32_e32 v95, v95, v165
	v_mul_f32_e32 v215, v215, v165
	s_branch .Lat_backg1b

; #define LAS __attribute__((address_space(3)))
; __device__ __forceinline__ int crow(int r, int hi) { return (r & 3) + 8 * (r >> 2) + 4 * hi; }
; template <int VAR>
; __device__ __forceinline__ void attn_unit(const Args& a, int l, int b, int h, int qrow0  , bool ctxu, const bf16* Z, bf16* Y, LAS unsigned char* lds) {
;     ...
;     LAS float* stg = (LAS float*)(lds + AT_ST) + wq * 2048;
;     if (comp == 1) {
; #pragma unroll
;         for (int r = 0; r < 16; ++r) { const int qr = crow(r, hi); const float il = lam * __builtin_amdgcn_rcpf(lacc[r]); stg[qr * 64 + r32] = o0[r] * il; stg[qr * 64 + 32 + r32] = o1[r] * il; }
.LBB0_459:
	s_lshl_b32 s9, s9, 13
	s_nop 5
	v_rcp_f32_e32 v68, v32
	v_rcp_f32_e32 v67, v33
	v_rcp_f32_e32 v66, v34
	v_rcp_f32_e32 v65, v35
	v_rcp_f32_e32 v64, v36
	v_rcp_f32_e32 v63, v37
	v_rcp_f32_e32 v62, v38
	v_rcp_f32_e32 v61, v39
	v_rcp_f32_e32 v60, v40
	v_rcp_f32_e32 v59, v41
	v_rcp_f32_e32 v58, v42
	v_rcp_f32_e32 v57, v43
	v_rcp_f32_e32 v56, v44
	v_rcp_f32_e32 v55, v45
	v_rcp_f32_e32 v54, v46
	v_rcp_f32_e32 v53, v47
	s_add_i32 s9, s9, 0
	s_add_i32 s9, s9, 0x11800
	v_lshlrev_b32_e32 v32, 10, v248
	v_lshlrev_b32_e32 v33, 2, v247
	s_cmp_eq_u32 s8, 1
	v_add3_u32 v52, s9, v32, v33
	s_cbranch_scc0 .LBB0_461
	v_add_u32_e32 v35, 0x800, v52
	v_mov_b32_e32 v32, v167
	v_mul_f32_e32 v33, v68, v32
	v_mul_f32_e32 v34, v0, v33
	v_mul_f32_e32 v33, v16, v33
	ds_write2_b32 v52, v34, v33 offset1:32
	v_mul_f32_e32 v33, v67, v32
	v_mul_f32_e32 v34, v1, v33
	v_mul_f32_e32 v33, v17, v33
	ds_write2_b32 v52, v34, v33 offset0:64 offset1:96
	v_mul_f32_e32 v33, v66, v32
	v_mul_f32_e32 v34, v2, v33
	v_mul_f32_e32 v33, v18, v33
	ds_write2_b32 v52, v34, v33 offset0:128 offset1:160
	v_mul_f32_e32 v33, v65, v32
	v_mul_f32_e32 v34, v3, v33
	v_mul_f32_e32 v33, v19, v33
	ds_write2_b32 v52, v34, v33 offset0:192 offset1:224
	v_mul_f32_e32 v33, v64, v32
	v_mul_f32_e32 v34, v4, v33
	v_mul_f32_e32 v33, v20, v33
	ds_write2_b32 v35, v34, v33 offset1:32
	v_mul_f32_e32 v33, v63, v32
	v_mul_f32_e32 v34, v5, v33
	v_mul_f32_e32 v33, v21, v33
	ds_write2_b32 v35, v34, v33 offset0:64 offset1:96
	v_mul_f32_e32 v33, v62, v32
	v_mul_f32_e32 v34, v6, v33
	v_mul_f32_e32 v33, v22, v33
	ds_write2_b32 v35, v34, v33 offset0:128 offset1:160
	v_mul_f32_e32 v33, v61, v32
	v_mul_f32_e32 v34, v7, v33
	v_mul_f32_e32 v33, v23, v33
	ds_write2_b32 v35, v34, v33 offset0:192 offset1:224
	v_mul_f32_e32 v33, v60, v32
	v_mul_f32_e32 v34, v8, v33
	v_mul_f32_e32 v33, v24, v33
	v_add_u32_e32 v35, 0x1000, v52
	ds_write2_b32 v35, v34, v33 offset1:32
	v_mul_f32_e32 v33, v59, v32
	v_mul_f32_e32 v34, v9, v33
	v_mul_f32_e32 v33, v25, v33
	ds_write2_b32 v35, v34, v33 offset0:64 offset1:96
	v_mul_f32_e32 v33, v58, v32
	v_mul_f32_e32 v34, v10, v33
	v_mul_f32_e32 v33, v26, v33
	ds_write2_b32 v35, v34, v33 offset0:128 offset1:160
	v_mul_f32_e32 v33, v57, v32
	v_mul_f32_e32 v34, v11, v33
	v_mul_f32_e32 v33, v27, v33
	ds_write2_b32 v35, v34, v33 offset0:192 offset1:224
	v_mul_f32_e32 v33, v56, v32
	v_mul_f32_e32 v34, v12, v33
	v_mul_f32_e32 v33, v28, v33
	v_add_u32_e32 v35, 0x1800, v52
	ds_write2_b32 v35, v34, v33 offset1:32
	v_mul_f32_e32 v33, v55, v32
	v_mul_f32_e32 v34, v13, v33
	v_mul_f32_e32 v33, v29, v33
	ds_write2_b32 v35, v34, v33 offset0:64 offset1:96
	v_mul_f32_e32 v33, v54, v32
	v_mul_f32_e32 v34, v14, v33
	v_mul_f32_e32 v33, v30, v33
	v_mul_f32_e32 v32, v53, v32
	ds_write2_b32 v35, v34, v33 offset0:128 offset1:160
	v_mul_f32_e32 v33, v15, v32
	v_mul_f32_e32 v32, v31, v32
	ds_write2_b32 v35, v33, v32 offset0:192 offset1:224
